# v37 = v30 with all eight A-tile (activation) loads re-issued early in ks3 and only the four B (weight) loads left in ks0
# speedup vs baseline: 1.0085x; 1.0085x over previous
.LBB0_301:
	s_mul_hi_u32 s0, s55, s25
	s_mul_i32 s1, s0, s20
	s_sub_i32 s1, s55, s1
	s_add_i32 s8, s0, 1
	s_sub_i32 s12, s1, s20
	s_cmp_ge_u32 s1, s20
	s_cselect_b32 s0, s8, s0
	s_cselect_b32 s1, s12, s1
	s_add_i32 s8, s0, 1
	s_cmp_ge_u32 s1, s20
	s_cselect_b32 s0, s8, s0
	s_add_i32 s1, s0, s23
	s_mul_i32 s0, s0, s20
	s_sub_i32 s0, s55, s0
	s_add_i32 s0, s0, s19
	s_lshl_b32 s12, s1, 8
	s_lshl_b32 s8, s0, 7
	s_mov_b64 s[0:1], s[30:31]
	v_mov_b32_e32 v0, v177
	s_mov_b32 s13, s9
	v_mbcnt_lo_u32_b32 v0, -1, v0
	v_mbcnt_hi_u32_b32 v0, -1, v0
	v_add_u32_e32 v182, s33, v0
	s_lshl_b64 s[16:17], s[12:13], 11
	v_ashrrev_i32_e32 v0, 3, v182
	v_lshlrev_b32_e32 v1, 3, v182
	s_add_u32 s56, s14, s16
	v_and_b32_e32 v6, 56, v1
	v_lshlrev_b32_e32 v1, 11, v0
	s_addc_u32 s57, s15, s17
	v_lshl_or_b32 v176, v6, 1, v1
	v_mul_lo_u32 v7, v0, s21
	v_lshl_add_u64 v[0:1], s[56:57], 0, v[176:177]
	v_add_co_u32_e32 v2, vcc, s26, v0
	s_lshl_b64 s[58:59], s[8:9], 11
	s_nop 0
	v_addc_co_u32_e32 v3, vcc, 0, v1, vcc
	v_add_co_u32_e32 v4, vcc, s27, v0
	s_add_u32 s58, s30, s58
	s_nop 0
	v_addc_co_u32_e32 v5, vcc, 0, v1, vcc
	global_load_dwordx4 v[128:131], v[2:3], off
	global_load_dwordx4 v[132:135], v[4:5], off
	v_add_co_u32_e32 v2, vcc, s34, v0
	s_addc_u32 s59, s31, s59
	s_nop 0
	v_addc_co_u32_e32 v3, vcc, 0, v1, vcc
	v_add_co_u32_e32 v4, vcc, s35, v0
	v_lshl_add_u64 v[178:179], s[58:59], 0, v[176:177]
	s_nop 0
	v_addc_co_u32_e32 v5, vcc, 0, v1, vcc
	global_load_dwordx4 v[136:139], v[2:3], off
	global_load_dwordx4 v[144:147], v[4:5], off
	v_add_co_u32_e32 v2, vcc, s36, v0
	v_bfe_u32 v185, v182, 6, 1
	s_nop 0
	v_addc_co_u32_e32 v3, vcc, 0, v1, vcc
	v_add_co_u32_e32 v4, vcc, s37, v0
	v_and_b32_e32 v184, 31, v182
	s_nop 0
	v_addc_co_u32_e32 v5, vcc, 0, v1, vcc
	v_add_co_u32_e32 v0, vcc, s38, v0
	global_load_dwordx4 v[148:151], v[2:3], off
	global_load_dwordx4 v[152:155], v[4:5], off
	v_addc_co_u32_e32 v1, vcc, 0, v1, vcc
	v_add_co_u32_e32 v2, vcc, s26, v178
	global_load_dwordx4 v[164:167], v176, s[56:57]
	global_load_dwordx4 v[140:143], v176, s[58:59]
	v_addc_co_u32_e32 v3, vcc, 0, v179, vcc
	global_load_dwordx4 v[156:159], v[0:1], off
	global_load_dwordx4 v[160:163], v[2:3], off
	v_add_co_u32_e32 v0, vcc, s27, v178
	v_bfe_u32 v186, v182, 5, 1
	s_nop 0
	v_addc_co_u32_e32 v1, vcc, 0, v179, vcc
	v_add_co_u32_e32 v2, vcc, s34, v178
	s_add_u32 s16, s30, s16
	s_nop 0
	v_addc_co_u32_e32 v3, vcc, 0, v179, vcc
	global_load_dwordx4 v[168:171], v[0:1], off
	global_load_dwordx4 v[172:175], v[2:3], off
	v_and_b32_e32 v0, 0xfffff9f, v182
	v_lshl_or_b32 v2, v185, 6, v184
	v_mul_lo_u32 v3, v0, s39
	v_or_b32_e32 v0, 0x60, v182
	v_lshlrev_b32_e32 v1, 4, v186
	v_mul_lo_u32 v4, v0, s39
	v_mul_u32_u24_e32 v2, 0x90, v2
	s_addc_u32 s17, s31, s17
	v_mov_b32_e32 v0, 0
	v_add_lshl_u32 v189, v7, v6, 1
	v_lshl_add_u64 v[180:181], s[16:17], 0, v[176:177]
	s_mov_b64 s[16:17], 0
	v_add_u32_e32 v188, v1, v3
	v_add_u32_e32 v187, v1, v4
	v_add_u32_e32 v176, v1, v2
	v_mov_b32_e32 v1, v0
	v_mov_b32_e32 v2, v0
	v_mov_b32_e32 v3, v0
	v_mov_b32_e32 v4, v0
	v_mov_b32_e32 v5, v0
	v_mov_b32_e32 v6, v0
	v_mov_b32_e32 v7, v0
	v_mov_b32_e32 v8, v0
	v_mov_b32_e32 v9, v0
	v_mov_b32_e32 v10, v0
	v_mov_b32_e32 v11, v0
	v_mov_b32_e32 v12, v0
	v_mov_b32_e32 v13, v0
	v_mov_b32_e32 v14, v0
	v_mov_b32_e32 v15, v0
	v_mov_b32_e32 v16, v0
	v_mov_b32_e32 v17, v0
	v_mov_b32_e32 v18, v0
	v_mov_b32_e32 v19, v0
	v_mov_b32_e32 v20, v0
	v_mov_b32_e32 v21, v0
	v_mov_b32_e32 v22, v0
	v_mov_b32_e32 v23, v0
	v_mov_b32_e32 v24, v0
	v_mov_b32_e32 v25, v0
	v_mov_b32_e32 v26, v0
	v_mov_b32_e32 v27, v0
	v_mov_b32_e32 v28, v0
	v_mov_b32_e32 v29, v0
	v_mov_b32_e32 v30, v0
	v_mov_b32_e32 v31, v0
	v_mov_b32_e32 v32, v0
	v_mov_b32_e32 v33, v0
	v_mov_b32_e32 v34, v0
	v_mov_b32_e32 v35, v0
	v_mov_b32_e32 v36, v0
	v_mov_b32_e32 v37, v0
	v_mov_b32_e32 v38, v0
	v_mov_b32_e32 v39, v0
	v_mov_b32_e32 v40, v0
	v_mov_b32_e32 v41, v0
	v_mov_b32_e32 v42, v0
	v_mov_b32_e32 v43, v0
	v_mov_b32_e32 v44, v0
	v_mov_b32_e32 v45, v0
	v_mov_b32_e32 v46, v0
	v_mov_b32_e32 v47, v0
	v_mov_b32_e32 v48, v0
	v_mov_b32_e32 v49, v0
	v_mov_b32_e32 v50, v0
	v_mov_b32_e32 v51, v0
	v_mov_b32_e32 v52, v0
	v_mov_b32_e32 v53, v0
	v_mov_b32_e32 v54, v0
	v_mov_b32_e32 v55, v0
	v_mov_b32_e32 v56, v0
	v_mov_b32_e32 v57, v0
	v_mov_b32_e32 v58, v0
	v_mov_b32_e32 v59, v0
	v_mov_b32_e32 v60, v0
	v_mov_b32_e32 v61, v0
	v_mov_b32_e32 v62, v0
	v_mov_b32_e32 v63, v0
	v_mov_b32_e32 v64, v0
	v_mov_b32_e32 v65, v0
	v_mov_b32_e32 v66, v0
	v_mov_b32_e32 v67, v0
	v_mov_b32_e32 v68, v0
	v_mov_b32_e32 v69, v0
	v_mov_b32_e32 v70, v0
	v_mov_b32_e32 v71, v0
	v_mov_b32_e32 v72, v0
	v_mov_b32_e32 v73, v0
	v_mov_b32_e32 v74, v0
	v_mov_b32_e32 v75, v0
	v_mov_b32_e32 v76, v0
	v_mov_b32_e32 v77, v0
	v_mov_b32_e32 v78, v0
	v_mov_b32_e32 v79, v0
	v_mov_b32_e32 v80, v0
	v_mov_b32_e32 v81, v0
	v_mov_b32_e32 v82, v0
	v_mov_b32_e32 v83, v0
	v_mov_b32_e32 v84, v0
	v_mov_b32_e32 v85, v0
	v_mov_b32_e32 v86, v0
	v_mov_b32_e32 v87, v0
	v_mov_b32_e32 v88, v0
	v_mov_b32_e32 v89, v0
	v_mov_b32_e32 v90, v0
	v_mov_b32_e32 v91, v0
	v_mov_b32_e32 v92, v0
	v_mov_b32_e32 v93, v0
	v_mov_b32_e32 v94, v0
	v_mov_b32_e32 v95, v0
	v_mov_b32_e32 v96, v0
	v_mov_b32_e32 v97, v0
	v_mov_b32_e32 v98, v0
	v_mov_b32_e32 v99, v0
	v_mov_b32_e32 v100, v0
	v_mov_b32_e32 v101, v0
	v_mov_b32_e32 v102, v0
	v_mov_b32_e32 v103, v0
	v_mov_b32_e32 v104, v0
	v_mov_b32_e32 v105, v0
	v_mov_b32_e32 v106, v0
	v_mov_b32_e32 v107, v0
	v_mov_b32_e32 v108, v0
	v_mov_b32_e32 v109, v0
	v_mov_b32_e32 v110, v0
	v_mov_b32_e32 v111, v0
	v_mov_b32_e32 v112, v0
	v_mov_b32_e32 v113, v0
	v_mov_b32_e32 v114, v0
	v_mov_b32_e32 v115, v0
	v_mov_b32_e32 v116, v0
	v_mov_b32_e32 v117, v0
	v_mov_b32_e32 v118, v0
	v_mov_b32_e32 v119, v0
	v_mov_b32_e32 v120, v0
	v_mov_b32_e32 v121, v0
	v_mov_b32_e32 v122, v0
	v_mov_b32_e32 v123, v0
	v_mov_b32_e32 v124, v0
	v_mov_b32_e32 v125, v0
	v_mov_b32_e32 v126, v0
	v_mov_b32_e32 v127, v0
	v_readfirstlane_b32 s40, v180
	v_readfirstlane_b32 s41, v181
	v_readfirstlane_b32 s42, v178
	v_readfirstlane_b32 s43, v179
	v_lshrrev_b32_e32 v198, 3, v182
	v_and_b32_e32 v199, 7, v182
	v_lshlrev_b32_e32 v198, 11, v198
	v_lshl_or_b32 v190, v199, 4, v198
	s_lshl_b32 s44, s33, 8
	s_sub_u32 s40, s40, s44
	s_subb_u32 s41, s41, 0
	s_sub_u32 s42, s42, s44
	s_subb_u32 s43, s43, 0
	s_add_u32 s40, s40, 0x2957980
	s_addc_u32 s41, s41, 0
	s_add_u32 s42, s42, 0x80
	s_addc_u32 s43, s43, 0
	v_add_u32_e32 v191, 0x10000, v190
	v_add_u32_e32 v192, 0x20000, v190
	v_add_u32_e32 v193, 0x30000, v190
	v_add_u32_e32 v194, 0x40000, v190
	v_add_u32_e32 v195, 0x50000, v190
	v_add_u32_e32 v196, 0x60000, v190
	v_add_u32_e32 v197, 0x70000, v190
	s_waitcnt lgkmcnt(0)
	s_barrier
	s_waitcnt vmcnt(0)
	ds_write_b128 v189, v[164:167]
	ds_write_b128 v189, v[128:131] offset:4608
	ds_write_b128 v189, v[132:135] offset:9216
	ds_write_b128 v189, v[136:139] offset:13824
	ds_write_b128 v189, v[144:147] offset:18432
	ds_write_b128 v189, v[148:151] offset:23040
	ds_write_b128 v189, v[152:155] offset:27648
	ds_write_b128 v189, v[156:159] offset:32256
	ds_write_b128 v189, v[140:143] offset:36864
	ds_write_b128 v189, v[160:163] offset:41472
	ds_write_b128 v189, v[168:171] offset:46080
	ds_write_b128 v189, v[172:175] offset:50688
	global_load_dwordx4 v[164:167], v190, s[40:41]
	global_load_dwordx4 v[128:131], v191, s[40:41]
	global_load_dwordx4 v[132:135], v192, s[40:41]
	global_load_dwordx4 v[136:139], v193, s[40:41]
	global_load_dwordx4 v[144:147], v194, s[40:41]
	global_load_dwordx4 v[148:151], v195, s[40:41]
	global_load_dwordx4 v[152:155], v196, s[40:41]
	global_load_dwordx4 v[156:159], v197, s[40:41]
	s_waitcnt lgkmcnt(0)
	s_barrier
.LBB0_302:
	ds_read_b128 v[216:219], v176 offset:36864
	ds_read_b128 v[200:203], v188
	ds_read_b128 v[220:223], v176 offset:41472
	ds_read_b128 v[204:207], v188 offset:4608
	ds_read_b128 v[208:211], v188 offset:9216
	ds_read_b128 v[212:215], v187
	s_waitcnt lgkmcnt(4)
	v_mfma_f32_32x32x16_bf16 v[112:127], v[200:203], v[216:219], v[112:127]
	ds_read_b128 v[240:243], v176 offset:36896
	global_load_dwordx4 v[140:143], v190, s[42:43]
	s_waitcnt lgkmcnt(4)
	v_mfma_f32_32x32x16_bf16 v[96:111], v[200:203], v[220:223], v[96:111]
	ds_read_b128 v[224:227], v188 offset:32
	global_load_dwordx4 v[160:163], v191, s[42:43]
	s_waitcnt lgkmcnt(4)
	v_mfma_f32_32x32x16_bf16 v[80:95], v[204:207], v[216:219], v[80:95]
	ds_read_b128 v[244:247], v176 offset:41504
	global_load_dwordx4 v[168:171], v192, s[42:43]
	s_waitcnt lgkmcnt(5)
	v_mfma_f32_32x32x16_bf16 v[64:79], v[204:207], v[220:223], v[64:79]
	ds_read_b128 v[228:231], v188 offset:4640
	global_load_dwordx4 v[172:175], v193, s[42:43]
	s_add_u32 s40, s40, 0x80
	s_addc_u32 s41, s41, 0
	s_add_u32 s42, s42, 0x80
	s_addc_u32 s43, s43, 0
	s_add_u32 s16, s16, 0x80
	s_waitcnt lgkmcnt(5)
	v_mfma_f32_32x32x16_bf16 v[48:63], v[208:211], v[216:219], v[48:63]
	ds_read_b128 v[232:235], v188 offset:9248
	s_waitcnt lgkmcnt(6)
	v_mfma_f32_32x32x16_bf16 v[32:47], v[208:211], v[220:223], v[32:47]
	ds_read_b128 v[236:239], v187 offset:32
	s_waitcnt lgkmcnt(6)
	v_mfma_f32_32x32x16_bf16 v[16:31], v[212:215], v[216:219], v[16:31]
	s_waitcnt lgkmcnt(6)
	v_mfma_f32_32x32x16_bf16 v[0:15], v[212:215], v[220:223], v[0:15]
	s_waitcnt lgkmcnt(4)
	v_mfma_f32_32x32x16_bf16 v[112:127], v[224:227], v[240:243], v[112:127]
	ds_read_b128 v[200:203], v188 offset:64
	s_waitcnt lgkmcnt(4)
	v_mfma_f32_32x32x16_bf16 v[96:111], v[224:227], v[244:247], v[96:111]
	ds_read_b128 v[204:207], v188 offset:4672
	s_waitcnt lgkmcnt(4)
	v_mfma_f32_32x32x16_bf16 v[80:95], v[228:231], v[240:243], v[80:95]
	ds_read_b128 v[208:211], v188 offset:9280
	s_waitcnt lgkmcnt(5)
	v_mfma_f32_32x32x16_bf16 v[64:79], v[228:231], v[244:247], v[64:79]
	ds_read_b128 v[212:215], v187 offset:64
	s_waitcnt lgkmcnt(5)
	v_mfma_f32_32x32x16_bf16 v[48:63], v[232:235], v[240:243], v[48:63]
	ds_read_b128 v[216:219], v176 offset:36928
	s_waitcnt lgkmcnt(6)
	v_mfma_f32_32x32x16_bf16 v[32:47], v[232:235], v[244:247], v[32:47]
	ds_read_b128 v[220:223], v176 offset:41536
	s_waitcnt lgkmcnt(6)
	v_mfma_f32_32x32x16_bf16 v[16:31], v[236:239], v[240:243], v[16:31]
	s_waitcnt lgkmcnt(6)
	v_mfma_f32_32x32x16_bf16 v[0:15], v[236:239], v[244:247], v[0:15]
	s_waitcnt lgkmcnt(1)
	v_mfma_f32_32x32x16_bf16 v[112:127], v[200:203], v[216:219], v[112:127]
	ds_read_b128 v[224:227], v188 offset:96
	s_waitcnt lgkmcnt(1)
	v_mfma_f32_32x32x16_bf16 v[96:111], v[200:203], v[220:223], v[96:111]
	ds_read_b128 v[228:231], v188 offset:4704
	s_waitcnt lgkmcnt(3)
	v_mfma_f32_32x32x16_bf16 v[80:95], v[204:207], v[216:219], v[80:95]
	ds_read_b128 v[232:235], v188 offset:9312
	s_waitcnt lgkmcnt(3)
	v_mfma_f32_32x32x16_bf16 v[64:79], v[204:207], v[220:223], v[64:79]
	ds_read_b128 v[236:239], v187 offset:96
	s_waitcnt lgkmcnt(5)
	v_mfma_f32_32x32x16_bf16 v[48:63], v[208:211], v[216:219], v[48:63]
	ds_read_b128 v[240:243], v176 offset:36960
	s_waitcnt lgkmcnt(5)
	v_mfma_f32_32x32x16_bf16 v[32:47], v[208:211], v[220:223], v[32:47]
	ds_read_b128 v[244:247], v176 offset:41568
	s_waitcnt lgkmcnt(7)
	v_mfma_f32_32x32x16_bf16 v[16:31], v[212:215], v[216:219], v[16:31]
	s_waitcnt lgkmcnt(6)
	v_mfma_f32_32x32x16_bf16 v[0:15], v[212:215], v[220:223], v[0:15]
	s_waitcnt lgkmcnt(0)
	s_barrier
	s_waitcnt vmcnt(4)
	s_waitcnt lgkmcnt(1)
	v_mfma_f32_32x32x16_bf16 v[112:127], v[224:227], v[240:243], v[112:127]
	ds_write_b128 v189, v[164:167]
	ds_write_b128 v189, v[128:131] offset:4608
	s_waitcnt lgkmcnt(2)
	v_mfma_f32_32x32x16_bf16 v[96:111], v[224:227], v[244:247], v[96:111]
	ds_write_b128 v189, v[132:135] offset:9216
	global_load_dwordx4 v[164:167], v190, s[40:41]
	s_waitcnt lgkmcnt(4)
	v_mfma_f32_32x32x16_bf16 v[80:95], v[228:231], v[240:243], v[80:95]
	ds_write_b128 v189, v[136:139] offset:13824
	ds_write_b128 v189, v[144:147] offset:18432
	global_load_dwordx4 v[128:131], v191, s[40:41]
	s_waitcnt lgkmcnt(5)
	v_mfma_f32_32x32x16_bf16 v[64:79], v[228:231], v[244:247], v[64:79]
	ds_write_b128 v189, v[148:151] offset:23040
	global_load_dwordx4 v[132:135], v192, s[40:41]
	s_waitcnt lgkmcnt(7)
	v_mfma_f32_32x32x16_bf16 v[48:63], v[232:235], v[240:243], v[48:63]
	ds_write_b128 v189, v[152:155] offset:27648
	ds_write_b128 v189, v[156:159] offset:32256
	global_load_dwordx4 v[136:139], v193, s[40:41]
	s_waitcnt lgkmcnt(8)
	v_mfma_f32_32x32x16_bf16 v[32:47], v[232:235], v[244:247], v[32:47]
	s_waitcnt vmcnt(4)
	ds_write_b128 v189, v[140:143] offset:36864
	global_load_dwordx4 v[144:147], v194, s[40:41]
	s_waitcnt lgkmcnt(10)
	v_mfma_f32_32x32x16_bf16 v[16:31], v[236:239], v[240:243], v[16:31]
	ds_write_b128 v189, v[160:163] offset:41472
	ds_write_b128 v189, v[168:171] offset:46080
	global_load_dwordx4 v[148:151], v195, s[40:41]
	s_waitcnt lgkmcnt(11)
	v_mfma_f32_32x32x16_bf16 v[0:15], v[236:239], v[244:247], v[0:15]
	ds_write_b128 v189, v[172:175] offset:50688
	global_load_dwordx4 v[152:155], v196, s[40:41]
	global_load_dwordx4 v[156:159], v197, s[40:41]
	s_waitcnt lgkmcnt(0)
	s_barrier
	s_cmpk_lg_i32 s16, 0x780
	s_cbranch_scc1 .LBB0_302
	ds_read_b128 v[216:219], v176 offset:36864
	ds_read_b128 v[200:203], v188
	ds_read_b128 v[220:223], v176 offset:41472
	ds_read_b128 v[204:207], v188 offset:4608
	ds_read_b128 v[208:211], v188 offset:9216
	ds_read_b128 v[212:215], v187
	s_waitcnt lgkmcnt(4)
	v_mfma_f32_32x32x16_bf16 v[112:127], v[200:203], v[216:219], v[112:127]
	ds_read_b128 v[240:243], v176 offset:36896
	s_waitcnt lgkmcnt(4)
	v_mfma_f32_32x32x16_bf16 v[96:111], v[200:203], v[220:223], v[96:111]
	ds_read_b128 v[224:227], v188 offset:32
	s_waitcnt lgkmcnt(4)
	v_mfma_f32_32x32x16_bf16 v[80:95], v[204:207], v[216:219], v[80:95]
	ds_read_b128 v[244:247], v176 offset:41504
	s_waitcnt lgkmcnt(5)
	v_mfma_f32_32x32x16_bf16 v[64:79], v[204:207], v[220:223], v[64:79]
	ds_read_b128 v[228:231], v188 offset:4640
	s_waitcnt lgkmcnt(5)
	v_mfma_f32_32x32x16_bf16 v[48:63], v[208:211], v[216:219], v[48:63]
	ds_read_b128 v[232:235], v188 offset:9248
	s_waitcnt lgkmcnt(6)
	v_mfma_f32_32x32x16_bf16 v[32:47], v[208:211], v[220:223], v[32:47]
	ds_read_b128 v[236:239], v187 offset:32
	s_waitcnt lgkmcnt(6)
	v_mfma_f32_32x32x16_bf16 v[16:31], v[212:215], v[216:219], v[16:31]
	s_waitcnt lgkmcnt(6)
	v_mfma_f32_32x32x16_bf16 v[0:15], v[212:215], v[220:223], v[0:15]
	s_waitcnt lgkmcnt(4)
	v_mfma_f32_32x32x16_bf16 v[112:127], v[224:227], v[240:243], v[112:127]
	ds_read_b128 v[200:203], v188 offset:64
	s_waitcnt lgkmcnt(4)
	v_mfma_f32_32x32x16_bf16 v[96:111], v[224:227], v[244:247], v[96:111]
	ds_read_b128 v[204:207], v188 offset:4672
	s_waitcnt lgkmcnt(4)
	v_mfma_f32_32x32x16_bf16 v[80:95], v[228:231], v[240:243], v[80:95]
	ds_read_b128 v[208:211], v188 offset:9280
	s_waitcnt lgkmcnt(5)
	v_mfma_f32_32x32x16_bf16 v[64:79], v[228:231], v[244:247], v[64:79]
	ds_read_b128 v[212:215], v187 offset:64
	s_waitcnt lgkmcnt(5)
	v_mfma_f32_32x32x16_bf16 v[48:63], v[232:235], v[240:243], v[48:63]
	ds_read_b128 v[216:219], v176 offset:36928
	s_waitcnt lgkmcnt(6)
	v_mfma_f32_32x32x16_bf16 v[32:47], v[232:235], v[244:247], v[32:47]
	ds_read_b128 v[220:223], v176 offset:41536
	s_waitcnt lgkmcnt(6)
	v_mfma_f32_32x32x16_bf16 v[16:31], v[236:239], v[240:243], v[16:31]
	s_waitcnt lgkmcnt(6)
	v_mfma_f32_32x32x16_bf16 v[0:15], v[236:239], v[244:247], v[0:15]
	s_waitcnt lgkmcnt(1)
	v_mfma_f32_32x32x16_bf16 v[112:127], v[200:203], v[216:219], v[112:127]
	ds_read_b128 v[224:227], v188 offset:96
	s_waitcnt lgkmcnt(1)
	v_mfma_f32_32x32x16_bf16 v[96:111], v[200:203], v[220:223], v[96:111]
	ds_read_b128 v[228:231], v188 offset:4704
	s_waitcnt lgkmcnt(3)
	v_mfma_f32_32x32x16_bf16 v[80:95], v[204:207], v[216:219], v[80:95]
	ds_read_b128 v[232:235], v188 offset:9312
	s_waitcnt lgkmcnt(3)
	v_mfma_f32_32x32x16_bf16 v[64:79], v[204:207], v[220:223], v[64:79]
	ds_read_b128 v[236:239], v187 offset:96
	s_waitcnt lgkmcnt(5)
	v_mfma_f32_32x32x16_bf16 v[48:63], v[208:211], v[216:219], v[48:63]
	ds_read_b128 v[240:243], v176 offset:36960
	s_waitcnt lgkmcnt(5)
	v_mfma_f32_32x32x16_bf16 v[32:47], v[208:211], v[220:223], v[32:47]
	ds_read_b128 v[244:247], v176 offset:41568
	s_waitcnt lgkmcnt(7)
	v_mfma_f32_32x32x16_bf16 v[16:31], v[212:215], v[216:219], v[16:31]
	s_waitcnt lgkmcnt(6)
	v_mfma_f32_32x32x16_bf16 v[0:15], v[212:215], v[220:223], v[0:15]
	s_waitcnt lgkmcnt(1)
	v_mfma_f32_32x32x16_bf16 v[112:127], v[224:227], v[240:243], v[112:127]
	s_waitcnt lgkmcnt(0)
	v_mfma_f32_32x32x16_bf16 v[96:111], v[224:227], v[244:247], v[96:111]
	s_waitcnt lgkmcnt(1)
	v_mfma_f32_32x32x16_bf16 v[80:95], v[228:231], v[240:243], v[80:95]
	s_waitcnt lgkmcnt(0)
	v_mfma_f32_32x32x16_bf16 v[64:79], v[228:231], v[244:247], v[64:79]
	s_waitcnt lgkmcnt(1)
	v_mfma_f32_32x32x16_bf16 v[48:63], v[232:235], v[240:243], v[48:63]
	s_waitcnt lgkmcnt(0)
	v_mfma_f32_32x32x16_bf16 v[32:47], v[232:235], v[244:247], v[32:47]
	s_waitcnt lgkmcnt(1)
	v_mfma_f32_32x32x16_bf16 v[16:31], v[236:239], v[240:243], v[16:31]
	s_waitcnt lgkmcnt(0)
	v_mfma_f32_32x32x16_bf16 v[0:15], v[236:239], v[244:247], v[0:15]
	s_waitcnt vmcnt(0)
	s_mul_i32 s44, s12, 0x1240
	s_add_u32 s40, s30, s44
	s_addc_u32 s41, s31, 0
	s_lshl_b32 s44, s8, 1
	s_add_u32 s40, s40, s44
	s_addc_u32 s41, s41, 0
	s_add_u32 s40, s40, 0x7157900
	s_addc_u32 s41, s41, 0
	v_and_b32_e32 v131, 15, v182
	v_lshrrev_b32_e32 v172, 4, v182
	v_lshl_add_u32 v130, v131, 3, s8
	s_movk_i32 s44, 0x920
	v_cmp_gt_u32_e64 s[42:43], s44, v130
	v_mul_u32_u24_e32 v164, 0x1240, v172
	v_lshl_add_u32 v164, v131, 4, v164
	v_add_u32_e32 v165, 0x12400, v164
	v_add_u32_e32 v166, 0x24800, v164
	v_add_u32_e32 v167, 0x36c00, v164
	v_add_u32_e32 v168, 0x92000, v164
	v_add_u32_e32 v169, 0xa4400, v164
	v_add_u32_e32 v170, 0xb6800, v164
	v_add_u32_e32 v171, 0xc8c00, v164
	v_mul_u32_u24_e32 v129, 0x110, v172
	v_lshl_add_u32 v129, v131, 4, v129
	v_lshrrev_b32_e32 v131, 7, v182
	v_bfe_u32 v172, v182, 5, 1
	v_lshlrev_b32_e32 v131, 6, v131
	v_lshl_or_b32 v131, v172, 2, v131
	v_mul_u32_u24_e32 v131, 136, v131
	v_and_b32_e32 v172, 0x5f, v182
	v_add_lshl_u32 v128, v131, v172, 1
	s_barrier
	v_cvt_pk_bf16_f32 v112, v112, v113
	v_cvt_pk_bf16_f32 v114, v114, v115
	v_cvt_pk_bf16_f32 v116, v116, v117
	v_cvt_pk_bf16_f32 v118, v118, v119
	v_cvt_pk_bf16_f32 v120, v120, v121
	v_cvt_pk_bf16_f32 v122, v122, v123
	v_cvt_pk_bf16_f32 v124, v124, v125
	v_cvt_pk_bf16_f32 v126, v126, v127
	v_cvt_pk_bf16_f32 v96, v96, v97
	v_cvt_pk_bf16_f32 v98, v98, v99
	v_cvt_pk_bf16_f32 v100, v100, v101
	v_cvt_pk_bf16_f32 v102, v102, v103
	v_cvt_pk_bf16_f32 v104, v104, v105
	v_cvt_pk_bf16_f32 v106, v106, v107
	v_cvt_pk_bf16_f32 v108, v108, v109
	v_cvt_pk_bf16_f32 v110, v110, v111
	v_cvt_pk_bf16_f32 v80, v80, v81
	v_cvt_pk_bf16_f32 v82, v82, v83
	v_cvt_pk_bf16_f32 v84, v84, v85
	v_cvt_pk_bf16_f32 v86, v86, v87
	v_cvt_pk_bf16_f32 v88, v88, v89
	v_cvt_pk_bf16_f32 v90, v90, v91
	v_cvt_pk_bf16_f32 v92, v92, v93
	v_cvt_pk_bf16_f32 v94, v94, v95
	v_cvt_pk_bf16_f32 v64, v64, v65
	v_cvt_pk_bf16_f32 v66, v66, v67
	v_cvt_pk_bf16_f32 v68, v68, v69
	v_cvt_pk_bf16_f32 v70, v70, v71
	v_cvt_pk_bf16_f32 v72, v72, v73
	v_cvt_pk_bf16_f32 v74, v74, v75
	v_cvt_pk_bf16_f32 v76, v76, v77
	v_cvt_pk_bf16_f32 v78, v78, v79
	ds_write_b16 v128, v112
	ds_write_b16_d16_hi v128, v112 offset:272
	ds_write_b16 v128, v114 offset:544
	ds_write_b16_d16_hi v128, v114 offset:816
	ds_write_b16 v128, v116 offset:2176
	ds_write_b16_d16_hi v128, v116 offset:2448
	ds_write_b16 v128, v118 offset:2720
	ds_write_b16_d16_hi v128, v118 offset:2992
	ds_write_b16 v128, v120 offset:4352
	ds_write_b16_d16_hi v128, v120 offset:4624
	ds_write_b16 v128, v122 offset:4896
	ds_write_b16_d16_hi v128, v122 offset:5168
	ds_write_b16 v128, v124 offset:6528
	ds_write_b16_d16_hi v128, v124 offset:6800
	ds_write_b16 v128, v126 offset:7072
	ds_write_b16_d16_hi v128, v126 offset:7344
	ds_write_b16 v128, v96 offset:64
	ds_write_b16_d16_hi v128, v96 offset:336
	ds_write_b16 v128, v98 offset:608
	ds_write_b16_d16_hi v128, v98 offset:880
	ds_write_b16 v128, v100 offset:2240
	ds_write_b16_d16_hi v128, v100 offset:2512
	ds_write_b16 v128, v102 offset:2784
	ds_write_b16_d16_hi v128, v102 offset:3056
	ds_write_b16 v128, v104 offset:4416
	ds_write_b16_d16_hi v128, v104 offset:4688
	ds_write_b16 v128, v106 offset:4960
	ds_write_b16_d16_hi v128, v106 offset:5232
	ds_write_b16 v128, v108 offset:6592
	ds_write_b16_d16_hi v128, v108 offset:6864
	ds_write_b16 v128, v110 offset:7136
	ds_write_b16_d16_hi v128, v110 offset:7408
	ds_write_b16 v128, v80 offset:8704
	ds_write_b16_d16_hi v128, v80 offset:8976
	ds_write_b16 v128, v82 offset:9248
	ds_write_b16_d16_hi v128, v82 offset:9520
	ds_write_b16 v128, v84 offset:10880
	ds_write_b16_d16_hi v128, v84 offset:11152
	ds_write_b16 v128, v86 offset:11424
	ds_write_b16_d16_hi v128, v86 offset:11696
	ds_write_b16 v128, v88 offset:13056
	ds_write_b16_d16_hi v128, v88 offset:13328
	ds_write_b16 v128, v90 offset:13600
	ds_write_b16_d16_hi v128, v90 offset:13872
	ds_write_b16 v128, v92 offset:15232
	ds_write_b16_d16_hi v128, v92 offset:15504
	ds_write_b16 v128, v94 offset:15776
	ds_write_b16_d16_hi v128, v94 offset:16048
	ds_write_b16 v128, v64 offset:8768
	ds_write_b16_d16_hi v128, v64 offset:9040
	ds_write_b16 v128, v66 offset:9312
	ds_write_b16_d16_hi v128, v66 offset:9584
	ds_write_b16 v128, v68 offset:10944
	ds_write_b16_d16_hi v128, v68 offset:11216
	ds_write_b16 v128, v70 offset:11488
	ds_write_b16_d16_hi v128, v70 offset:11760
	ds_write_b16 v128, v72 offset:13120
	ds_write_b16_d16_hi v128, v72 offset:13392
	ds_write_b16 v128, v74 offset:13664
	ds_write_b16_d16_hi v128, v74 offset:13936
	ds_write_b16 v128, v76 offset:15296
	ds_write_b16_d16_hi v128, v76 offset:15568
	ds_write_b16 v128, v78 offset:15840
	ds_write_b16_d16_hi v128, v78 offset:16112
	s_waitcnt lgkmcnt(0)
	s_barrier
	ds_read_b128 v[132:135], v129
	ds_read_b128 v[136:139], v129 offset:4352
	ds_read_b128 v[140:143], v129 offset:8704
	ds_read_b128 v[144:147], v129 offset:13056
	ds_read_b128 v[148:151], v129 offset:17408
	ds_read_b128 v[152:155], v129 offset:21760
	ds_read_b128 v[156:159], v129 offset:26112
	ds_read_b128 v[160:163], v129 offset:30464
	v_cvt_pk_bf16_f32 v48, v48, v49
	v_cvt_pk_bf16_f32 v50, v50, v51
	v_cvt_pk_bf16_f32 v52, v52, v53
	v_cvt_pk_bf16_f32 v54, v54, v55
	v_cvt_pk_bf16_f32 v56, v56, v57
	v_cvt_pk_bf16_f32 v58, v58, v59
	v_cvt_pk_bf16_f32 v60, v60, v61
	v_cvt_pk_bf16_f32 v62, v62, v63
	v_cvt_pk_bf16_f32 v32, v32, v33
	v_cvt_pk_bf16_f32 v34, v34, v35
	v_cvt_pk_bf16_f32 v36, v36, v37
	v_cvt_pk_bf16_f32 v38, v38, v39
	v_cvt_pk_bf16_f32 v40, v40, v41
	v_cvt_pk_bf16_f32 v42, v42, v43
	v_cvt_pk_bf16_f32 v44, v44, v45
	v_cvt_pk_bf16_f32 v46, v46, v47
	v_cvt_pk_bf16_f32 v16, v16, v17
	v_cvt_pk_bf16_f32 v18, v18, v19
	v_cvt_pk_bf16_f32 v20, v20, v21
	v_cvt_pk_bf16_f32 v22, v22, v23
	v_cvt_pk_bf16_f32 v24, v24, v25
	v_cvt_pk_bf16_f32 v26, v26, v27
	v_cvt_pk_bf16_f32 v28, v28, v29
	v_cvt_pk_bf16_f32 v30, v30, v31
	v_cvt_pk_bf16_f32 v0, v0, v1
	v_cvt_pk_bf16_f32 v2, v2, v3
	v_cvt_pk_bf16_f32 v4, v4, v5
	v_cvt_pk_bf16_f32 v6, v6, v7
	v_cvt_pk_bf16_f32 v8, v8, v9
	v_cvt_pk_bf16_f32 v10, v10, v11
	v_cvt_pk_bf16_f32 v12, v12, v13
	v_cvt_pk_bf16_f32 v14, v14, v15
	s_and_saveexec_b64 s[46:47], s[42:43]
	s_waitcnt lgkmcnt(7)
	global_store_dwordx4 v164, v[132:135], s[40:41]
	s_waitcnt lgkmcnt(6)
	global_store_dwordx4 v165, v[136:139], s[40:41]
	s_waitcnt lgkmcnt(5)
	global_store_dwordx4 v166, v[140:143], s[40:41]
	s_waitcnt lgkmcnt(4)
	global_store_dwordx4 v167, v[144:147], s[40:41]
	s_waitcnt lgkmcnt(3)
	global_store_dwordx4 v168, v[148:151], s[40:41]
	s_waitcnt lgkmcnt(2)
	global_store_dwordx4 v169, v[152:155], s[40:41]
	s_waitcnt lgkmcnt(1)
	global_store_dwordx4 v170, v[156:159], s[40:41]
	s_waitcnt lgkmcnt(0)
	global_store_dwordx4 v171, v[160:163], s[40:41]
	s_or_b64 exec, exec, s[46:47]
	s_barrier
	ds_write_b16 v128, v48
	ds_write_b16_d16_hi v128, v48 offset:272
	ds_write_b16 v128, v50 offset:544
	ds_write_b16_d16_hi v128, v50 offset:816
	ds_write_b16 v128, v52 offset:2176
	ds_write_b16_d16_hi v128, v52 offset:2448
	ds_write_b16 v128, v54 offset:2720
	ds_write_b16_d16_hi v128, v54 offset:2992
	ds_write_b16 v128, v56 offset:4352
	ds_write_b16_d16_hi v128, v56 offset:4624
	ds_write_b16 v128, v58 offset:4896
	ds_write_b16_d16_hi v128, v58 offset:5168
	ds_write_b16 v128, v60 offset:6528
	ds_write_b16_d16_hi v128, v60 offset:6800
	ds_write_b16 v128, v62 offset:7072
	ds_write_b16_d16_hi v128, v62 offset:7344
	ds_write_b16 v128, v32 offset:64
	ds_write_b16_d16_hi v128, v32 offset:336
	ds_write_b16 v128, v34 offset:608
	ds_write_b16_d16_hi v128, v34 offset:880
	ds_write_b16 v128, v36 offset:2240
	ds_write_b16_d16_hi v128, v36 offset:2512
	ds_write_b16 v128, v38 offset:2784
	ds_write_b16_d16_hi v128, v38 offset:3056
	ds_write_b16 v128, v40 offset:4416
	ds_write_b16_d16_hi v128, v40 offset:4688
	ds_write_b16 v128, v42 offset:4960
	ds_write_b16_d16_hi v128, v42 offset:5232
	ds_write_b16 v128, v44 offset:6592
	ds_write_b16_d16_hi v128, v44 offset:6864
	ds_write_b16 v128, v46 offset:7136
	ds_write_b16_d16_hi v128, v46 offset:7408
	ds_write_b16 v128, v16 offset:8704
	ds_write_b16_d16_hi v128, v16 offset:8976
	ds_write_b16 v128, v18 offset:9248
	ds_write_b16_d16_hi v128, v18 offset:9520
	ds_write_b16 v128, v20 offset:10880
	ds_write_b16_d16_hi v128, v20 offset:11152
	ds_write_b16 v128, v22 offset:11424
	ds_write_b16_d16_hi v128, v22 offset:11696
	ds_write_b16 v128, v24 offset:13056
	ds_write_b16_d16_hi v128, v24 offset:13328
	ds_write_b16 v128, v26 offset:13600
	ds_write_b16_d16_hi v128, v26 offset:13872
	ds_write_b16 v128, v28 offset:15232
	ds_write_b16_d16_hi v128, v28 offset:15504
	ds_write_b16 v128, v30 offset:15776
	ds_write_b16_d16_hi v128, v30 offset:16048
	ds_write_b16 v128, v0 offset:8768
	ds_write_b16_d16_hi v128, v0 offset:9040
	ds_write_b16 v128, v2 offset:9312
	ds_write_b16_d16_hi v128, v2 offset:9584
	ds_write_b16 v128, v4 offset:10944
	ds_write_b16_d16_hi v128, v4 offset:11216
	ds_write_b16 v128, v6 offset:11488
	ds_write_b16_d16_hi v128, v6 offset:11760
	ds_write_b16 v128, v8 offset:13120
	ds_write_b16_d16_hi v128, v8 offset:13392
	ds_write_b16 v128, v10 offset:13664
	ds_write_b16_d16_hi v128, v10 offset:13936
	ds_write_b16 v128, v12 offset:15296
	ds_write_b16_d16_hi v128, v12 offset:15568
	ds_write_b16 v128, v14 offset:15840
	ds_write_b16_d16_hi v128, v14 offset:16112
	s_waitcnt lgkmcnt(0)
	s_barrier
	ds_read_b128 v[132:135], v129
	ds_read_b128 v[136:139], v129 offset:4352
	ds_read_b128 v[140:143], v129 offset:8704
	ds_read_b128 v[144:147], v129 offset:13056
	ds_read_b128 v[148:151], v129 offset:17408
	ds_read_b128 v[152:155], v129 offset:21760
	ds_read_b128 v[156:159], v129 offset:26112
	ds_read_b128 v[160:163], v129 offset:30464
	v_add_u32_e32 v164, 0x49000, v164
	v_add_u32_e32 v165, 0x49000, v165
	v_add_u32_e32 v166, 0x49000, v166
	v_add_u32_e32 v167, 0x49000, v167
	v_add_u32_e32 v168, 0x49000, v168
	v_add_u32_e32 v169, 0x49000, v169
	v_add_u32_e32 v170, 0x49000, v170
	v_add_u32_e32 v171, 0x49000, v171
	s_and_saveexec_b64 s[46:47], s[42:43]
	s_waitcnt lgkmcnt(7)
	global_store_dwordx4 v164, v[132:135], s[40:41]
	s_waitcnt lgkmcnt(6)
	global_store_dwordx4 v165, v[136:139], s[40:41]
	s_waitcnt lgkmcnt(5)
	global_store_dwordx4 v166, v[140:143], s[40:41]
	s_waitcnt lgkmcnt(4)
	global_store_dwordx4 v167, v[144:147], s[40:41]
	s_waitcnt lgkmcnt(3)
	global_store_dwordx4 v168, v[148:151], s[40:41]
	s_waitcnt lgkmcnt(2)
	global_store_dwordx4 v169, v[152:155], s[40:41]
	s_waitcnt lgkmcnt(1)
	global_store_dwordx4 v170, v[156:159], s[40:41]
	s_waitcnt lgkmcnt(0)
	global_store_dwordx4 v171, v[160:163], s[40:41]
	s_or_b64 exec, exec, s[46:47]
	s_branch .Lmt4_tail_0

.Lv5_c_1:
	ds_write_b128 v189, v[160:163]
	ds_write_b128 v189, v[128:131] offset:4608
	ds_write_b128 v189, v[132:135] offset:9216
	ds_write_b128 v189, v[136:139] offset:13824
	ds_write_b128 v189, v[140:143] offset:18432
	ds_write_b128 v189, v[144:147] offset:23040
	ds_write_b128 v189, v[148:151] offset:27648
	ds_write_b128 v189, v[156:159] offset:32256
	ds_write_b128 v189, v[152:155] offset:36864
	ds_write_b128 v189, v[164:167] offset:41472
	ds_write_b128 v189, v[168:171] offset:46080
	ds_write_b128 v189, v[172:175] offset:50688
	global_load_dwordx4 v[160:163], v190, s[38:39]
	global_load_dwordx4 v[128:131], v191, s[38:39]
	global_load_dwordx4 v[132:135], v192, s[38:39]
	global_load_dwordx4 v[136:139], v193, s[38:39]
	global_load_dwordx4 v[140:143], v194, s[38:39]
	global_load_dwordx4 v[144:147], v195, s[38:39]
	global_load_dwordx4 v[148:151], v196, s[38:39]
	global_load_dwordx4 v[156:159], v197, s[38:39]
	s_waitcnt lgkmcnt(0)
	s_barrier
.LBB0_997:
	ds_read_b128 v[216:219], v188 offset:36864
	ds_read_b128 v[200:203], v187
	ds_read_b128 v[220:223], v188 offset:41472
	ds_read_b128 v[204:207], v187 offset:4608
	ds_read_b128 v[208:211], v187 offset:9216
	ds_read_b128 v[212:215], v176
	s_waitcnt lgkmcnt(4)
	v_mfma_f32_32x32x16_bf16 v[112:127], v[200:203], v[216:219], v[112:127]
	ds_read_b128 v[240:243], v188 offset:36896
	global_load_dwordx4 v[152:155], v190, s[40:41]
	s_waitcnt lgkmcnt(4)
	v_mfma_f32_32x32x16_bf16 v[96:111], v[200:203], v[220:223], v[96:111]
	ds_read_b128 v[224:227], v187 offset:32
	global_load_dwordx4 v[164:167], v191, s[40:41]
	s_waitcnt lgkmcnt(4)
	v_mfma_f32_32x32x16_bf16 v[80:95], v[204:207], v[216:219], v[80:95]
	ds_read_b128 v[244:247], v188 offset:41504
	global_load_dwordx4 v[168:171], v192, s[40:41]
	s_waitcnt lgkmcnt(5)
	v_mfma_f32_32x32x16_bf16 v[64:79], v[204:207], v[220:223], v[64:79]
	ds_read_b128 v[228:231], v187 offset:4640
	global_load_dwordx4 v[172:175], v193, s[40:41]
	s_add_u32 s38, s38, 0x80
	s_addc_u32 s39, s39, 0
	s_add_u32 s40, s40, 0x80
	s_addc_u32 s41, s41, 0
	s_add_u32 s12, s12, 0x80
	s_waitcnt lgkmcnt(5)
	v_mfma_f32_32x32x16_bf16 v[48:63], v[208:211], v[216:219], v[48:63]
	ds_read_b128 v[232:235], v187 offset:9248
	s_waitcnt lgkmcnt(6)
	v_mfma_f32_32x32x16_bf16 v[32:47], v[208:211], v[220:223], v[32:47]
	ds_read_b128 v[236:239], v176 offset:32
	s_waitcnt lgkmcnt(6)
	v_mfma_f32_32x32x16_bf16 v[16:31], v[212:215], v[216:219], v[16:31]
	s_waitcnt lgkmcnt(6)
	v_mfma_f32_32x32x16_bf16 v[0:15], v[212:215], v[220:223], v[0:15]
	s_waitcnt lgkmcnt(4)
	v_mfma_f32_32x32x16_bf16 v[112:127], v[224:227], v[240:243], v[112:127]
	ds_read_b128 v[200:203], v187 offset:64
	s_waitcnt lgkmcnt(4)
	v_mfma_f32_32x32x16_bf16 v[96:111], v[224:227], v[244:247], v[96:111]
	ds_read_b128 v[204:207], v187 offset:4672
	s_waitcnt lgkmcnt(4)
	v_mfma_f32_32x32x16_bf16 v[80:95], v[228:231], v[240:243], v[80:95]
	ds_read_b128 v[208:211], v187 offset:9280
	s_waitcnt lgkmcnt(5)
	v_mfma_f32_32x32x16_bf16 v[64:79], v[228:231], v[244:247], v[64:79]
	ds_read_b128 v[212:215], v176 offset:64
	s_waitcnt lgkmcnt(5)
	v_mfma_f32_32x32x16_bf16 v[48:63], v[232:235], v[240:243], v[48:63]
	ds_read_b128 v[216:219], v188 offset:36928
	s_waitcnt lgkmcnt(6)
	v_mfma_f32_32x32x16_bf16 v[32:47], v[232:235], v[244:247], v[32:47]
	ds_read_b128 v[220:223], v188 offset:41536
	s_waitcnt lgkmcnt(6)
	v_mfma_f32_32x32x16_bf16 v[16:31], v[236:239], v[240:243], v[16:31]
	s_waitcnt lgkmcnt(6)
	v_mfma_f32_32x32x16_bf16 v[0:15], v[236:239], v[244:247], v[0:15]
	s_waitcnt lgkmcnt(1)
	v_mfma_f32_32x32x16_bf16 v[112:127], v[200:203], v[216:219], v[112:127]
	ds_read_b128 v[224:227], v187 offset:96
	s_waitcnt lgkmcnt(1)
	v_mfma_f32_32x32x16_bf16 v[96:111], v[200:203], v[220:223], v[96:111]
	ds_read_b128 v[228:231], v187 offset:4704
	s_waitcnt lgkmcnt(3)
	v_mfma_f32_32x32x16_bf16 v[80:95], v[204:207], v[216:219], v[80:95]
	ds_read_b128 v[232:235], v187 offset:9312
	s_waitcnt lgkmcnt(3)
	v_mfma_f32_32x32x16_bf16 v[64:79], v[204:207], v[220:223], v[64:79]
	ds_read_b128 v[236:239], v176 offset:96
	s_waitcnt lgkmcnt(5)
	v_mfma_f32_32x32x16_bf16 v[48:63], v[208:211], v[216:219], v[48:63]
	ds_read_b128 v[240:243], v188 offset:36960
	s_waitcnt lgkmcnt(5)
	v_mfma_f32_32x32x16_bf16 v[32:47], v[208:211], v[220:223], v[32:47]
	ds_read_b128 v[244:247], v188 offset:41568
	s_waitcnt lgkmcnt(7)
	v_mfma_f32_32x32x16_bf16 v[16:31], v[212:215], v[216:219], v[16:31]
	s_waitcnt lgkmcnt(6)
	v_mfma_f32_32x32x16_bf16 v[0:15], v[212:215], v[220:223], v[0:15]
	s_waitcnt lgkmcnt(0)
	s_barrier
	s_waitcnt vmcnt(4)
	s_waitcnt lgkmcnt(1)
	v_mfma_f32_32x32x16_bf16 v[112:127], v[224:227], v[240:243], v[112:127]
	ds_write_b128 v189, v[160:163]
	ds_write_b128 v189, v[128:131] offset:4608
	s_waitcnt lgkmcnt(2)
	v_mfma_f32_32x32x16_bf16 v[96:111], v[224:227], v[244:247], v[96:111]
	ds_write_b128 v189, v[132:135] offset:9216
	global_load_dwordx4 v[160:163], v190, s[38:39]
	s_waitcnt lgkmcnt(4)
	v_mfma_f32_32x32x16_bf16 v[80:95], v[228:231], v[240:243], v[80:95]
	ds_write_b128 v189, v[136:139] offset:13824
	ds_write_b128 v189, v[140:143] offset:18432
	global_load_dwordx4 v[128:131], v191, s[38:39]
	s_waitcnt lgkmcnt(5)
	v_mfma_f32_32x32x16_bf16 v[64:79], v[228:231], v[244:247], v[64:79]
	ds_write_b128 v189, v[144:147] offset:23040
	global_load_dwordx4 v[132:135], v192, s[38:39]
	s_waitcnt lgkmcnt(7)
	v_mfma_f32_32x32x16_bf16 v[48:63], v[232:235], v[240:243], v[48:63]
	ds_write_b128 v189, v[148:151] offset:27648
	ds_write_b128 v189, v[156:159] offset:32256
	global_load_dwordx4 v[136:139], v193, s[38:39]
	s_waitcnt lgkmcnt(8)
	v_mfma_f32_32x32x16_bf16 v[32:47], v[232:235], v[244:247], v[32:47]
	s_waitcnt vmcnt(4)
	ds_write_b128 v189, v[152:155] offset:36864
	global_load_dwordx4 v[140:143], v194, s[38:39]
	s_waitcnt lgkmcnt(10)
	v_mfma_f32_32x32x16_bf16 v[16:31], v[236:239], v[240:243], v[16:31]
	ds_write_b128 v189, v[164:167] offset:41472
	ds_write_b128 v189, v[168:171] offset:46080
	global_load_dwordx4 v[144:147], v195, s[38:39]
	s_waitcnt lgkmcnt(11)
	v_mfma_f32_32x32x16_bf16 v[0:15], v[236:239], v[244:247], v[0:15]
	ds_write_b128 v189, v[172:175] offset:50688
	global_load_dwordx4 v[148:151], v196, s[38:39]
	global_load_dwordx4 v[156:159], v197, s[38:39]
	s_waitcnt lgkmcnt(0)
	s_barrier
	s_cmpk_lg_i32 s12, 0x780
	s_cbranch_scc1 .LBB0_997
	ds_read_b128 v[216:219], v188 offset:36864
	ds_read_b128 v[200:203], v187
	ds_read_b128 v[220:223], v188 offset:41472
	ds_read_b128 v[204:207], v187 offset:4608
	ds_read_b128 v[208:211], v187 offset:9216
	ds_read_b128 v[212:215], v176
	s_waitcnt lgkmcnt(4)
	v_mfma_f32_32x32x16_bf16 v[112:127], v[200:203], v[216:219], v[112:127]
	ds_read_b128 v[240:243], v188 offset:36896
	s_waitcnt lgkmcnt(4)
	v_mfma_f32_32x32x16_bf16 v[96:111], v[200:203], v[220:223], v[96:111]
	ds_read_b128 v[224:227], v187 offset:32
	s_waitcnt lgkmcnt(4)
	v_mfma_f32_32x32x16_bf16 v[80:95], v[204:207], v[216:219], v[80:95]
	ds_read_b128 v[244:247], v188 offset:41504
	s_waitcnt lgkmcnt(5)
	v_mfma_f32_32x32x16_bf16 v[64:79], v[204:207], v[220:223], v[64:79]
	ds_read_b128 v[228:231], v187 offset:4640
	s_waitcnt lgkmcnt(5)
	v_mfma_f32_32x32x16_bf16 v[48:63], v[208:211], v[216:219], v[48:63]
	ds_read_b128 v[232:235], v187 offset:9248
	s_waitcnt lgkmcnt(6)
	v_mfma_f32_32x32x16_bf16 v[32:47], v[208:211], v[220:223], v[32:47]
	ds_read_b128 v[236:239], v176 offset:32
	s_waitcnt lgkmcnt(6)
	v_mfma_f32_32x32x16_bf16 v[16:31], v[212:215], v[216:219], v[16:31]
	s_waitcnt lgkmcnt(6)
	v_mfma_f32_32x32x16_bf16 v[0:15], v[212:215], v[220:223], v[0:15]
	s_waitcnt lgkmcnt(4)
	v_mfma_f32_32x32x16_bf16 v[112:127], v[224:227], v[240:243], v[112:127]
	ds_read_b128 v[200:203], v187 offset:64
	s_waitcnt lgkmcnt(4)
	v_mfma_f32_32x32x16_bf16 v[96:111], v[224:227], v[244:247], v[96:111]
	ds_read_b128 v[204:207], v187 offset:4672
	s_waitcnt lgkmcnt(4)
	v_mfma_f32_32x32x16_bf16 v[80:95], v[228:231], v[240:243], v[80:95]
	ds_read_b128 v[208:211], v187 offset:9280
	s_waitcnt lgkmcnt(5)
	v_mfma_f32_32x32x16_bf16 v[64:79], v[228:231], v[244:247], v[64:79]
	ds_read_b128 v[212:215], v176 offset:64
	s_waitcnt lgkmcnt(5)
	v_mfma_f32_32x32x16_bf16 v[48:63], v[232:235], v[240:243], v[48:63]
	ds_read_b128 v[216:219], v188 offset:36928
	s_waitcnt lgkmcnt(6)
	v_mfma_f32_32x32x16_bf16 v[32:47], v[232:235], v[244:247], v[32:47]
	ds_read_b128 v[220:223], v188 offset:41536
	s_waitcnt lgkmcnt(6)
	v_mfma_f32_32x32x16_bf16 v[16:31], v[236:239], v[240:243], v[16:31]
	s_waitcnt lgkmcnt(6)
	v_mfma_f32_32x32x16_bf16 v[0:15], v[236:239], v[244:247], v[0:15]
	s_waitcnt lgkmcnt(1)
	v_mfma_f32_32x32x16_bf16 v[112:127], v[200:203], v[216:219], v[112:127]
	ds_read_b128 v[224:227], v187 offset:96
	s_waitcnt lgkmcnt(1)
	v_mfma_f32_32x32x16_bf16 v[96:111], v[200:203], v[220:223], v[96:111]
	ds_read_b128 v[228:231], v187 offset:4704
	s_waitcnt lgkmcnt(3)
	v_mfma_f32_32x32x16_bf16 v[80:95], v[204:207], v[216:219], v[80:95]
	ds_read_b128 v[232:235], v187 offset:9312
	s_waitcnt lgkmcnt(3)
	v_mfma_f32_32x32x16_bf16 v[64:79], v[204:207], v[220:223], v[64:79]
	ds_read_b128 v[236:239], v176 offset:96
	s_waitcnt lgkmcnt(5)
	v_mfma_f32_32x32x16_bf16 v[48:63], v[208:211], v[216:219], v[48:63]
	ds_read_b128 v[240:243], v188 offset:36960
	s_waitcnt lgkmcnt(5)
	v_mfma_f32_32x32x16_bf16 v[32:47], v[208:211], v[220:223], v[32:47]
	ds_read_b128 v[244:247], v188 offset:41568
	s_waitcnt lgkmcnt(7)
	v_mfma_f32_32x32x16_bf16 v[16:31], v[212:215], v[216:219], v[16:31]
	s_waitcnt lgkmcnt(6)
	v_mfma_f32_32x32x16_bf16 v[0:15], v[212:215], v[220:223], v[0:15]
	s_waitcnt lgkmcnt(1)
	v_mfma_f32_32x32x16_bf16 v[112:127], v[224:227], v[240:243], v[112:127]
	s_waitcnt lgkmcnt(0)
	v_mfma_f32_32x32x16_bf16 v[96:111], v[224:227], v[244:247], v[96:111]
	s_waitcnt lgkmcnt(1)
	v_mfma_f32_32x32x16_bf16 v[80:95], v[228:231], v[240:243], v[80:95]
	s_waitcnt lgkmcnt(0)
	v_mfma_f32_32x32x16_bf16 v[64:79], v[228:231], v[244:247], v[64:79]
	s_waitcnt lgkmcnt(1)
	v_mfma_f32_32x32x16_bf16 v[48:63], v[232:235], v[240:243], v[48:63]
	s_waitcnt lgkmcnt(0)
	v_mfma_f32_32x32x16_bf16 v[32:47], v[232:235], v[244:247], v[32:47]
	s_waitcnt lgkmcnt(1)
	v_mfma_f32_32x32x16_bf16 v[16:31], v[236:239], v[240:243], v[16:31]
	s_waitcnt lgkmcnt(0)
	v_mfma_f32_32x32x16_bf16 v[0:15], v[236:239], v[244:247], v[0:15]
	s_waitcnt vmcnt(0)
	s_mul_i32 s42, s6, 0x2000
	s_add_u32 s44, s30, s42
	s_addc_u32 s45, s31, 0
	s_lshl_b32 s42, s58, 1
	s_add_u32 s44, s44, s42
	s_addc_u32 s45, s45, 0
	s_add_u32 s44, s44, 0x7157900
	s_addc_u32 s45, s45, 0
	s_mov_b32 s43, 1
	v_max_f32_e32 v112, 0, v112
	v_max_f32_e32 v113, 0, v113
	v_mul_f32_e32 v112, v112, v112
	v_mul_f32_e32 v113, v113, v113
	v_cvt_pk_bf16_f32 v190, v112, v113
	v_max_f32_e32 v114, 0, v114
	v_max_f32_e32 v115, 0, v115
	v_mul_f32_e32 v114, v114, v114
	v_mul_f32_e32 v115, v115, v115
	v_cvt_pk_bf16_f32 v191, v114, v115
	v_max_f32_e32 v116, 0, v116
	v_max_f32_e32 v117, 0, v117
	v_mul_f32_e32 v116, v116, v116
	v_mul_f32_e32 v117, v117, v117
	v_cvt_pk_bf16_f32 v192, v116, v117
	v_max_f32_e32 v118, 0, v118
	v_max_f32_e32 v119, 0, v119
	v_mul_f32_e32 v118, v118, v118
	v_mul_f32_e32 v119, v119, v119
	v_cvt_pk_bf16_f32 v193, v118, v119
	v_max_f32_e32 v120, 0, v120
	v_max_f32_e32 v121, 0, v121
	v_mul_f32_e32 v120, v120, v120
	v_mul_f32_e32 v121, v121, v121
	v_cvt_pk_bf16_f32 v194, v120, v121
	v_max_f32_e32 v122, 0, v122
	v_max_f32_e32 v123, 0, v123
	v_mul_f32_e32 v122, v122, v122
	v_mul_f32_e32 v123, v123, v123
	v_cvt_pk_bf16_f32 v195, v122, v123
	v_max_f32_e32 v124, 0, v124
	v_max_f32_e32 v125, 0, v125
	v_mul_f32_e32 v124, v124, v124
	v_mul_f32_e32 v125, v125, v125
	v_cvt_pk_bf16_f32 v196, v124, v125
	v_max_f32_e32 v126, 0, v126
	v_max_f32_e32 v127, 0, v127
	v_mul_f32_e32 v126, v126, v126
	v_mul_f32_e32 v127, v127, v127
	v_cvt_pk_bf16_f32 v197, v126, v127
	v_max_f32_e32 v96, 0, v96
	v_max_f32_e32 v97, 0, v97
	v_mul_f32_e32 v96, v96, v96
	v_mul_f32_e32 v97, v97, v97
	v_cvt_pk_bf16_f32 v198, v96, v97
	v_max_f32_e32 v98, 0, v98
	v_max_f32_e32 v99, 0, v99
	v_mul_f32_e32 v98, v98, v98
	v_mul_f32_e32 v99, v99, v99
	v_cvt_pk_bf16_f32 v199, v98, v99
	v_max_f32_e32 v100, 0, v100
	v_max_f32_e32 v101, 0, v101
	v_mul_f32_e32 v100, v100, v100
	v_mul_f32_e32 v101, v101, v101
	v_cvt_pk_bf16_f32 v200, v100, v101
	v_max_f32_e32 v102, 0, v102
	v_max_f32_e32 v103, 0, v103
	v_mul_f32_e32 v102, v102, v102
	v_mul_f32_e32 v103, v103, v103
	v_cvt_pk_bf16_f32 v201, v102, v103
	v_max_f32_e32 v104, 0, v104
	v_max_f32_e32 v105, 0, v105
	v_mul_f32_e32 v104, v104, v104
	v_mul_f32_e32 v105, v105, v105
	v_cvt_pk_bf16_f32 v202, v104, v105
	v_max_f32_e32 v106, 0, v106
	v_max_f32_e32 v107, 0, v107
	v_mul_f32_e32 v106, v106, v106
	v_mul_f32_e32 v107, v107, v107
	v_cvt_pk_bf16_f32 v203, v106, v107
	v_max_f32_e32 v108, 0, v108
	v_max_f32_e32 v109, 0, v109
	v_mul_f32_e32 v108, v108, v108
	v_mul_f32_e32 v109, v109, v109
	v_cvt_pk_bf16_f32 v204, v108, v109
	v_max_f32_e32 v110, 0, v110
	v_max_f32_e32 v111, 0, v111
	v_mul_f32_e32 v110, v110, v110
	v_mul_f32_e32 v111, v111, v111
	v_cvt_pk_bf16_f32 v205, v110, v111
	v_max_f32_e32 v80, 0, v80
	v_max_f32_e32 v81, 0, v81
	v_mul_f32_e32 v80, v80, v80
	v_mul_f32_e32 v81, v81, v81
	v_cvt_pk_bf16_f32 v206, v80, v81
	v_max_f32_e32 v82, 0, v82
	v_max_f32_e32 v83, 0, v83
	v_mul_f32_e32 v82, v82, v82
	v_mul_f32_e32 v83, v83, v83
	v_cvt_pk_bf16_f32 v207, v82, v83
	v_max_f32_e32 v84, 0, v84
	v_max_f32_e32 v85, 0, v85
	v_mul_f32_e32 v84, v84, v84
	v_mul_f32_e32 v85, v85, v85
	v_cvt_pk_bf16_f32 v208, v84, v85
	v_max_f32_e32 v86, 0, v86
	v_max_f32_e32 v87, 0, v87
	v_mul_f32_e32 v86, v86, v86
	v_mul_f32_e32 v87, v87, v87
	v_cvt_pk_bf16_f32 v209, v86, v87
	v_max_f32_e32 v88, 0, v88
	v_max_f32_e32 v89, 0, v89
	v_mul_f32_e32 v88, v88, v88
	v_mul_f32_e32 v89, v89, v89
	v_cvt_pk_bf16_f32 v210, v88, v89
	v_max_f32_e32 v90, 0, v90
	v_max_f32_e32 v91, 0, v91
	v_mul_f32_e32 v90, v90, v90
	v_mul_f32_e32 v91, v91, v91
	v_cvt_pk_bf16_f32 v211, v90, v91
	v_max_f32_e32 v92, 0, v92
	v_max_f32_e32 v93, 0, v93
	v_mul_f32_e32 v92, v92, v92
	v_mul_f32_e32 v93, v93, v93
	v_cvt_pk_bf16_f32 v212, v92, v93
	v_max_f32_e32 v94, 0, v94
	v_max_f32_e32 v95, 0, v95
	v_mul_f32_e32 v94, v94, v94
	v_mul_f32_e32 v95, v95, v95
	v_cvt_pk_bf16_f32 v213, v94, v95
	v_max_f32_e32 v64, 0, v64
	v_max_f32_e32 v65, 0, v65
	v_mul_f32_e32 v64, v64, v64
	v_mul_f32_e32 v65, v65, v65
	v_cvt_pk_bf16_f32 v214, v64, v65
	v_max_f32_e32 v66, 0, v66
	v_max_f32_e32 v67, 0, v67
	v_mul_f32_e32 v66, v66, v66
	v_mul_f32_e32 v67, v67, v67
	v_cvt_pk_bf16_f32 v215, v66, v67
	v_max_f32_e32 v68, 0, v68
	v_max_f32_e32 v69, 0, v69
	v_mul_f32_e32 v68, v68, v68
	v_mul_f32_e32 v69, v69, v69
	v_cvt_pk_bf16_f32 v216, v68, v69
	v_max_f32_e32 v70, 0, v70
	v_max_f32_e32 v71, 0, v71
	v_mul_f32_e32 v70, v70, v70
	v_mul_f32_e32 v71, v71, v71
	v_cvt_pk_bf16_f32 v217, v70, v71
	v_max_f32_e32 v72, 0, v72
	v_max_f32_e32 v73, 0, v73
	v_mul_f32_e32 v72, v72, v72
	v_mul_f32_e32 v73, v73, v73
	v_cvt_pk_bf16_f32 v218, v72, v73
	v_max_f32_e32 v74, 0, v74
	v_max_f32_e32 v75, 0, v75
	v_mul_f32_e32 v74, v74, v74
	v_mul_f32_e32 v75, v75, v75
	v_cvt_pk_bf16_f32 v219, v74, v75
	v_max_f32_e32 v76, 0, v76
	v_max_f32_e32 v77, 0, v77
	v_mul_f32_e32 v76, v76, v76
	v_mul_f32_e32 v77, v77, v77
	v_cvt_pk_bf16_f32 v220, v76, v77
	v_max_f32_e32 v78, 0, v78
	v_max_f32_e32 v79, 0, v79
	v_mul_f32_e32 v78, v78, v78
	v_mul_f32_e32 v79, v79, v79
	v_cvt_pk_bf16_f32 v221, v78, v79
	v_max_f32_e32 v48, 0, v48
	v_max_f32_e32 v49, 0, v49
	v_mul_f32_e32 v48, v48, v48
	v_mul_f32_e32 v49, v49, v49
	v_cvt_pk_bf16_f32 v222, v48, v49
	v_max_f32_e32 v50, 0, v50
	v_max_f32_e32 v51, 0, v51
	v_mul_f32_e32 v50, v50, v50
	v_mul_f32_e32 v51, v51, v51
	v_cvt_pk_bf16_f32 v223, v50, v51
	v_max_f32_e32 v52, 0, v52
	v_max_f32_e32 v53, 0, v53
	v_mul_f32_e32 v52, v52, v52
	v_mul_f32_e32 v53, v53, v53
	v_cvt_pk_bf16_f32 v224, v52, v53
	v_max_f32_e32 v54, 0, v54
	v_max_f32_e32 v55, 0, v55
	v_mul_f32_e32 v54, v54, v54
	v_mul_f32_e32 v55, v55, v55
	v_cvt_pk_bf16_f32 v225, v54, v55
	v_max_f32_e32 v56, 0, v56
	v_max_f32_e32 v57, 0, v57
	v_mul_f32_e32 v56, v56, v56
	v_mul_f32_e32 v57, v57, v57
	v_cvt_pk_bf16_f32 v226, v56, v57
	v_max_f32_e32 v58, 0, v58
	v_max_f32_e32 v59, 0, v59
	v_mul_f32_e32 v58, v58, v58
	v_mul_f32_e32 v59, v59, v59
	v_cvt_pk_bf16_f32 v227, v58, v59
	v_max_f32_e32 v60, 0, v60
	v_max_f32_e32 v61, 0, v61
	v_mul_f32_e32 v60, v60, v60
	v_mul_f32_e32 v61, v61, v61
	v_cvt_pk_bf16_f32 v228, v60, v61
	v_max_f32_e32 v62, 0, v62
	v_max_f32_e32 v63, 0, v63
	v_mul_f32_e32 v62, v62, v62
	v_mul_f32_e32 v63, v63, v63
	v_cvt_pk_bf16_f32 v229, v62, v63
	v_max_f32_e32 v32, 0, v32
	v_max_f32_e32 v33, 0, v33
	v_mul_f32_e32 v32, v32, v32
	v_mul_f32_e32 v33, v33, v33
	v_cvt_pk_bf16_f32 v230, v32, v33
	v_max_f32_e32 v34, 0, v34
	v_max_f32_e32 v35, 0, v35
	v_mul_f32_e32 v34, v34, v34
	v_mul_f32_e32 v35, v35, v35
	v_cvt_pk_bf16_f32 v231, v34, v35
	v_max_f32_e32 v36, 0, v36
	v_max_f32_e32 v37, 0, v37
	v_mul_f32_e32 v36, v36, v36
	v_mul_f32_e32 v37, v37, v37
	v_cvt_pk_bf16_f32 v232, v36, v37
	v_max_f32_e32 v38, 0, v38
	v_max_f32_e32 v39, 0, v39
	v_mul_f32_e32 v38, v38, v38
	v_mul_f32_e32 v39, v39, v39
	v_cvt_pk_bf16_f32 v233, v38, v39
	v_max_f32_e32 v40, 0, v40
	v_max_f32_e32 v41, 0, v41
	v_mul_f32_e32 v40, v40, v40
	v_mul_f32_e32 v41, v41, v41
	v_cvt_pk_bf16_f32 v234, v40, v41
	v_max_f32_e32 v42, 0, v42
	v_max_f32_e32 v43, 0, v43
	v_mul_f32_e32 v42, v42, v42
	v_mul_f32_e32 v43, v43, v43
	v_cvt_pk_bf16_f32 v235, v42, v43
	v_max_f32_e32 v44, 0, v44
	v_max_f32_e32 v45, 0, v45
	v_mul_f32_e32 v44, v44, v44
	v_mul_f32_e32 v45, v45, v45
	v_cvt_pk_bf16_f32 v236, v44, v45
	v_max_f32_e32 v46, 0, v46
	v_max_f32_e32 v47, 0, v47
	v_mul_f32_e32 v46, v46, v46
	v_mul_f32_e32 v47, v47, v47
	v_cvt_pk_bf16_f32 v237, v46, v47
	v_max_f32_e32 v16, 0, v16
	v_max_f32_e32 v17, 0, v17
	v_mul_f32_e32 v16, v16, v16
	v_mul_f32_e32 v17, v17, v17
	v_cvt_pk_bf16_f32 v238, v16, v17
	v_max_f32_e32 v18, 0, v18
	v_max_f32_e32 v19, 0, v19
	v_mul_f32_e32 v18, v18, v18
	v_mul_f32_e32 v19, v19, v19
	v_cvt_pk_bf16_f32 v239, v18, v19
	v_max_f32_e32 v20, 0, v20
	v_max_f32_e32 v21, 0, v21
	v_mul_f32_e32 v20, v20, v20
	v_mul_f32_e32 v21, v21, v21
	v_cvt_pk_bf16_f32 v240, v20, v21
	v_max_f32_e32 v22, 0, v22
	v_max_f32_e32 v23, 0, v23
	v_mul_f32_e32 v22, v22, v22
	v_mul_f32_e32 v23, v23, v23
	v_cvt_pk_bf16_f32 v241, v22, v23
	v_max_f32_e32 v24, 0, v24
	v_max_f32_e32 v25, 0, v25
	v_mul_f32_e32 v24, v24, v24
	v_mul_f32_e32 v25, v25, v25
	v_cvt_pk_bf16_f32 v242, v24, v25
	v_max_f32_e32 v26, 0, v26
	v_max_f32_e32 v27, 0, v27
	v_mul_f32_e32 v26, v26, v26
	v_mul_f32_e32 v27, v27, v27
	v_cvt_pk_bf16_f32 v243, v26, v27
	v_max_f32_e32 v28, 0, v28
	v_max_f32_e32 v29, 0, v29
	v_mul_f32_e32 v28, v28, v28
	v_mul_f32_e32 v29, v29, v29
	v_cvt_pk_bf16_f32 v244, v28, v29
	v_max_f32_e32 v30, 0, v30
	v_max_f32_e32 v31, 0, v31
	v_mul_f32_e32 v30, v30, v30
	v_mul_f32_e32 v31, v31, v31
	v_cvt_pk_bf16_f32 v245, v30, v31
	v_max_f32_e32 v0, 0, v0
	v_max_f32_e32 v1, 0, v1
	v_mul_f32_e32 v0, v0, v0
	v_mul_f32_e32 v1, v1, v1
	v_cvt_pk_bf16_f32 v246, v0, v1
	v_max_f32_e32 v2, 0, v2
	v_max_f32_e32 v3, 0, v3
	v_mul_f32_e32 v2, v2, v2
	v_mul_f32_e32 v3, v3, v3
	v_cvt_pk_bf16_f32 v247, v2, v3
	v_max_f32_e32 v4, 0, v4
	v_max_f32_e32 v5, 0, v5
	v_mul_f32_e32 v4, v4, v4
	v_mul_f32_e32 v5, v5, v5
	v_cvt_pk_bf16_f32 v248, v4, v5
	v_max_f32_e32 v6, 0, v6
	v_max_f32_e32 v7, 0, v7
	v_mul_f32_e32 v6, v6, v6
	v_mul_f32_e32 v7, v7, v7
	v_cvt_pk_bf16_f32 v249, v6, v7
	v_max_f32_e32 v8, 0, v8
	v_max_f32_e32 v9, 0, v9
	v_mul_f32_e32 v8, v8, v8
	v_mul_f32_e32 v9, v9, v9
	v_cvt_pk_bf16_f32 v250, v8, v9
	v_max_f32_e32 v10, 0, v10
	v_max_f32_e32 v11, 0, v11
	v_mul_f32_e32 v10, v10, v10
	v_mul_f32_e32 v11, v11, v11
	v_cvt_pk_bf16_f32 v251, v10, v11
	v_max_f32_e32 v12, 0, v12
	v_max_f32_e32 v13, 0, v13
	v_mul_f32_e32 v12, v12, v12
	v_mul_f32_e32 v13, v13, v13
	v_cvt_pk_bf16_f32 v252, v12, v13
	v_max_f32_e32 v14, 0, v14
	v_max_f32_e32 v15, 0, v15
	v_mul_f32_e32 v14, v14, v14
	v_mul_f32_e32 v15, v15, v15
	v_cvt_pk_bf16_f32 v253, v14, v15
	s_add_i32 s57, s57, s22
	s_add_i32 s56, s56, s22
	s_cmpk_lt_u32 s57, 0x240
	s_cbranch_scc1 .LBB0_996
	v_and_b32_e32 v3, 15, v182
	v_lshrrev_b32_e32 v4, 4, v182
	v_mul_u32_u24_e32 v2, 0x2000, v4
	v_lshl_add_u32 v2, v3, 4, v2
	v_mul_u32_u24_e32 v1, 0x110, v4
	v_lshl_add_u32 v1, v3, 4, v1
	v_lshrrev_b32_e32 v3, 7, v182
	v_bfe_u32 v4, v182, 5, 1
	v_lshlrev_b32_e32 v3, 6, v3
	v_lshl_or_b32 v3, v4, 2, v3
	v_mul_u32_u24_e32 v3, 136, v3
	v_and_b32_e32 v4, 0x5f, v182
	v_add_lshl_u32 v0, v3, v4, 1
	s_barrier
	ds_write_b16 v0, v190
	ds_write_b16_d16_hi v0, v190 offset:272
	ds_write_b16 v0, v191 offset:544
	ds_write_b16_d16_hi v0, v191 offset:816
	ds_write_b16 v0, v192 offset:2176
	ds_write_b16_d16_hi v0, v192 offset:2448
	ds_write_b16 v0, v193 offset:2720
	ds_write_b16_d16_hi v0, v193 offset:2992
	ds_write_b16 v0, v194 offset:4352
	ds_write_b16_d16_hi v0, v194 offset:4624
	ds_write_b16 v0, v195 offset:4896
	ds_write_b16_d16_hi v0, v195 offset:5168
	ds_write_b16 v0, v196 offset:6528
	ds_write_b16_d16_hi v0, v196 offset:6800
	ds_write_b16 v0, v197 offset:7072
	ds_write_b16_d16_hi v0, v197 offset:7344
	ds_write_b16 v0, v198 offset:64
	ds_write_b16_d16_hi v0, v198 offset:336
	ds_write_b16 v0, v199 offset:608
	ds_write_b16_d16_hi v0, v199 offset:880
	ds_write_b16 v0, v200 offset:2240
	ds_write_b16_d16_hi v0, v200 offset:2512
	ds_write_b16 v0, v201 offset:2784
	ds_write_b16_d16_hi v0, v201 offset:3056
	ds_write_b16 v0, v202 offset:4416
	ds_write_b16_d16_hi v0, v202 offset:4688
	ds_write_b16 v0, v203 offset:4960
	ds_write_b16_d16_hi v0, v203 offset:5232
	ds_write_b16 v0, v204 offset:6592
	ds_write_b16_d16_hi v0, v204 offset:6864
	ds_write_b16 v0, v205 offset:7136
	ds_write_b16_d16_hi v0, v205 offset:7408
	ds_write_b16 v0, v206 offset:8704
	ds_write_b16_d16_hi v0, v206 offset:8976
	ds_write_b16 v0, v207 offset:9248
	ds_write_b16_d16_hi v0, v207 offset:9520
	ds_write_b16 v0, v208 offset:10880
	ds_write_b16_d16_hi v0, v208 offset:11152
	ds_write_b16 v0, v209 offset:11424
	ds_write_b16_d16_hi v0, v209 offset:11696
	ds_write_b16 v0, v210 offset:13056
	ds_write_b16_d16_hi v0, v210 offset:13328
	ds_write_b16 v0, v211 offset:13600
	ds_write_b16_d16_hi v0, v211 offset:13872
	ds_write_b16 v0, v212 offset:15232
	ds_write_b16_d16_hi v0, v212 offset:15504
	ds_write_b16 v0, v213 offset:15776
	ds_write_b16_d16_hi v0, v213 offset:16048
	ds_write_b16 v0, v214 offset:8768
	ds_write_b16_d16_hi v0, v214 offset:9040
	ds_write_b16 v0, v215 offset:9312
	ds_write_b16_d16_hi v0, v215 offset:9584
	ds_write_b16 v0, v216 offset:10944
	ds_write_b16_d16_hi v0, v216 offset:11216
	ds_write_b16 v0, v217 offset:11488
	ds_write_b16_d16_hi v0, v217 offset:11760
	ds_write_b16 v0, v218 offset:13120
	ds_write_b16_d16_hi v0, v218 offset:13392
	ds_write_b16 v0, v219 offset:13664
	ds_write_b16_d16_hi v0, v219 offset:13936
	ds_write_b16 v0, v220 offset:15296
	ds_write_b16_d16_hi v0, v220 offset:15568
	ds_write_b16 v0, v221 offset:15840
	ds_write_b16_d16_hi v0, v221 offset:16112
	s_waitcnt lgkmcnt(0)
	s_barrier
	ds_read_b128 v[8:11], v1
	ds_read_b128 v[12:15], v1 offset:4352
	ds_read_b128 v[16:19], v1 offset:8704
	ds_read_b128 v[20:23], v1 offset:13056
	ds_read_b128 v[24:27], v1 offset:17408
	ds_read_b128 v[28:31], v1 offset:21760
	ds_read_b128 v[32:35], v1 offset:26112
	ds_read_b128 v[36:39], v1 offset:30464
	s_add_u32 s38, s44, 0x0
	s_addc_u32 s39, s45, 0
	s_waitcnt lgkmcnt(7)
	global_store_dwordx4 v2, v[8:11], s[38:39]
	s_add_u32 s38, s44, 0x20000
	s_addc_u32 s39, s45, 0
	s_waitcnt lgkmcnt(6)
	global_store_dwordx4 v2, v[12:15], s[38:39]
	s_add_u32 s38, s44, 0x40000
	s_addc_u32 s39, s45, 0
	s_waitcnt lgkmcnt(5)
	global_store_dwordx4 v2, v[16:19], s[38:39]
	s_add_u32 s38, s44, 0x60000
	s_addc_u32 s39, s45, 0
	s_waitcnt lgkmcnt(4)
	global_store_dwordx4 v2, v[20:23], s[38:39]
	s_add_u32 s38, s44, 0x100000
	s_addc_u32 s39, s45, 0
	s_waitcnt lgkmcnt(3)
	global_store_dwordx4 v2, v[24:27], s[38:39]
	s_add_u32 s38, s44, 0x120000
	s_addc_u32 s39, s45, 0
	s_waitcnt lgkmcnt(2)
	global_store_dwordx4 v2, v[28:31], s[38:39]
	s_add_u32 s38, s44, 0x140000
	s_addc_u32 s39, s45, 0
	s_waitcnt lgkmcnt(1)
	global_store_dwordx4 v2, v[32:35], s[38:39]
	s_add_u32 s38, s44, 0x160000
	s_addc_u32 s39, s45, 0
	s_waitcnt lgkmcnt(0)
	global_store_dwordx4 v2, v[36:39], s[38:39]
	s_barrier
	ds_write_b16 v0, v222
	ds_write_b16_d16_hi v0, v222 offset:272
	ds_write_b16 v0, v223 offset:544
	ds_write_b16_d16_hi v0, v223 offset:816
	ds_write_b16 v0, v224 offset:2176
	ds_write_b16_d16_hi v0, v224 offset:2448
	ds_write_b16 v0, v225 offset:2720
	ds_write_b16_d16_hi v0, v225 offset:2992
	ds_write_b16 v0, v226 offset:4352
	ds_write_b16_d16_hi v0, v226 offset:4624
	ds_write_b16 v0, v227 offset:4896
	ds_write_b16_d16_hi v0, v227 offset:5168
	ds_write_b16 v0, v228 offset:6528
	ds_write_b16_d16_hi v0, v228 offset:6800
	ds_write_b16 v0, v229 offset:7072
	ds_write_b16_d16_hi v0, v229 offset:7344
	ds_write_b16 v0, v230 offset:64
	ds_write_b16_d16_hi v0, v230 offset:336
	ds_write_b16 v0, v231 offset:608
	ds_write_b16_d16_hi v0, v231 offset:880
	ds_write_b16 v0, v232 offset:2240
	ds_write_b16_d16_hi v0, v232 offset:2512
	ds_write_b16 v0, v233 offset:2784
	ds_write_b16_d16_hi v0, v233 offset:3056
	ds_write_b16 v0, v234 offset:4416
	ds_write_b16_d16_hi v0, v234 offset:4688
	ds_write_b16 v0, v235 offset:4960
	ds_write_b16_d16_hi v0, v235 offset:5232
	ds_write_b16 v0, v236 offset:6592
	ds_write_b16_d16_hi v0, v236 offset:6864
	ds_write_b16 v0, v237 offset:7136
	ds_write_b16_d16_hi v0, v237 offset:7408
	ds_write_b16 v0, v238 offset:8704
	ds_write_b16_d16_hi v0, v238 offset:8976
	ds_write_b16 v0, v239 offset:9248
	ds_write_b16_d16_hi v0, v239 offset:9520
	ds_write_b16 v0, v240 offset:10880
	ds_write_b16_d16_hi v0, v240 offset:11152
	ds_write_b16 v0, v241 offset:11424
	ds_write_b16_d16_hi v0, v241 offset:11696
	ds_write_b16 v0, v242 offset:13056
	ds_write_b16_d16_hi v0, v242 offset:13328
	ds_write_b16 v0, v243 offset:13600
	ds_write_b16_d16_hi v0, v243 offset:13872
	ds_write_b16 v0, v244 offset:15232
	ds_write_b16_d16_hi v0, v244 offset:15504
	ds_write_b16 v0, v245 offset:15776
	ds_write_b16_d16_hi v0, v245 offset:16048
	ds_write_b16 v0, v246 offset:8768
	ds_write_b16_d16_hi v0, v246 offset:9040
	ds_write_b16 v0, v247 offset:9312
	ds_write_b16_d16_hi v0, v247 offset:9584
	ds_write_b16 v0, v248 offset:10944
	ds_write_b16_d16_hi v0, v248 offset:11216
	ds_write_b16 v0, v249 offset:11488
	ds_write_b16_d16_hi v0, v249 offset:11760
	ds_write_b16 v0, v250 offset:13120
	ds_write_b16_d16_hi v0, v250 offset:13392
	ds_write_b16 v0, v251 offset:13664
	ds_write_b16_d16_hi v0, v251 offset:13936
	ds_write_b16 v0, v252 offset:15296
	ds_write_b16_d16_hi v0, v252 offset:15568
	ds_write_b16 v0, v253 offset:15840
	ds_write_b16_d16_hi v0, v253 offset:16112
	s_waitcnt lgkmcnt(0)
	s_barrier
	ds_read_b128 v[8:11], v1
	ds_read_b128 v[12:15], v1 offset:4352
	ds_read_b128 v[16:19], v1 offset:8704
	ds_read_b128 v[20:23], v1 offset:13056
	ds_read_b128 v[24:27], v1 offset:17408
	ds_read_b128 v[28:31], v1 offset:21760
	ds_read_b128 v[32:35], v1 offset:26112
	ds_read_b128 v[36:39], v1 offset:30464
	s_add_u32 s38, s44, 0x80000
	s_addc_u32 s39, s45, 0
	s_waitcnt lgkmcnt(7)
	global_store_dwordx4 v2, v[8:11], s[38:39]
	s_add_u32 s38, s44, 0xa0000
	s_addc_u32 s39, s45, 0
	s_waitcnt lgkmcnt(6)
	global_store_dwordx4 v2, v[12:15], s[38:39]
	s_add_u32 s38, s44, 0xc0000
	s_addc_u32 s39, s45, 0
	s_waitcnt lgkmcnt(5)
	global_store_dwordx4 v2, v[16:19], s[38:39]
	s_add_u32 s38, s44, 0xe0000
	s_addc_u32 s39, s45, 0
	s_waitcnt lgkmcnt(4)
	global_store_dwordx4 v2, v[20:23], s[38:39]
	s_add_u32 s38, s44, 0x180000
	s_addc_u32 s39, s45, 0
	s_waitcnt lgkmcnt(3)
	global_store_dwordx4 v2, v[24:27], s[38:39]
	s_add_u32 s38, s44, 0x1a0000
	s_addc_u32 s39, s45, 0
	s_waitcnt lgkmcnt(2)
	global_store_dwordx4 v2, v[28:31], s[38:39]
	s_add_u32 s38, s44, 0x1c0000
	s_addc_u32 s39, s45, 0
	s_waitcnt lgkmcnt(1)
	global_store_dwordx4 v2, v[32:35], s[38:39]
	s_add_u32 s38, s44, 0x1e0000
	s_addc_u32 s39, s45, 0
	s_waitcnt lgkmcnt(0)
	global_store_dwordx4 v2, v[36:39], s[38:39]
	s_mov_b32 s43, 0
	s_branch .LBB0_989

.LBB0_1282:
	s_mul_hi_u32 s0, s56, s25
	s_mul_i32 s1, s0, s20
	s_sub_i32 s1, s56, s1
	s_add_i32 s8, s0, 1
	s_sub_i32 s12, s1, s20
	s_cmp_ge_u32 s1, s20
	s_cselect_b32 s0, s8, s0
	s_cselect_b32 s1, s12, s1
	s_add_i32 s8, s0, 1
	s_cmp_ge_u32 s1, s20
	s_cselect_b32 s1, s8, s0
	s_add_i32 s0, s1, s23
	s_mul_i32 s1, s1, s20
	s_sub_i32 s1, s56, s1
	s_add_i32 s1, s1, s19
	s_mul_i32 s8, s0, 0xe38e3900
	v_alignbit_b32 v0, s8, s8, 8
	s_cmp_lt_u32 s1, 8
	v_cmp_gt_u32_e32 vcc, s26, v0
	s_cselect_b64 s[12:13], -1, 0
	s_and_b64 s[12:13], vcc, s[12:13]
	s_and_b64 vcc, exec, s[12:13]
	s_cbranch_vccnz .LBB0_1281
	s_lshl_b32 s12, s0, 8
	s_lshl_b32 s8, s1, 7
	s_mov_b64 s[0:1], s[30:31]
	v_mov_b32_e32 v0, v177
	s_mov_b32 s13, s9
	v_mbcnt_lo_u32_b32 v0, -1, v0
	v_mbcnt_hi_u32_b32 v0, -1, v0
	v_add_u32_e32 v182, s33, v0
	s_lshl_b64 s[16:17], s[12:13], 11
	v_ashrrev_i32_e32 v0, 3, v182
	v_lshlrev_b32_e32 v1, 3, v182
	s_add_u32 s58, s14, s16
	v_and_b32_e32 v6, 56, v1
	v_lshlrev_b32_e32 v1, 11, v0
	s_addc_u32 s59, s15, s17
	v_lshl_or_b32 v176, v6, 1, v1
	v_mul_lo_u32 v7, v0, s21
	v_lshl_add_u64 v[0:1], s[58:59], 0, v[176:177]
	v_add_co_u32_e32 v2, vcc, s27, v0
	s_lshl_b64 s[60:61], s[8:9], 11
	s_nop 0
	v_addc_co_u32_e32 v3, vcc, 0, v1, vcc
	v_add_co_u32_e32 v4, vcc, s34, v0
	s_add_u32 s60, s30, s60
	s_nop 0
	v_addc_co_u32_e32 v5, vcc, 0, v1, vcc
	global_load_dwordx4 v[128:131], v[2:3], off
	global_load_dwordx4 v[132:135], v[4:5], off
	v_add_co_u32_e32 v2, vcc, s35, v0
	s_addc_u32 s61, s31, s61
	s_nop 0
	v_addc_co_u32_e32 v3, vcc, 0, v1, vcc
	v_add_co_u32_e32 v4, vcc, s36, v0
	v_lshl_add_u64 v[178:179], s[60:61], 0, v[176:177]
	s_nop 0
	v_addc_co_u32_e32 v5, vcc, 0, v1, vcc
	global_load_dwordx4 v[136:139], v[2:3], off
	global_load_dwordx4 v[144:147], v[4:5], off
	v_add_co_u32_e32 v2, vcc, s37, v0
	v_bfe_u32 v185, v182, 6, 1
	s_nop 0
	v_addc_co_u32_e32 v3, vcc, 0, v1, vcc
	v_add_co_u32_e32 v4, vcc, s38, v0
	v_and_b32_e32 v184, 31, v182
	s_nop 0
	v_addc_co_u32_e32 v5, vcc, 0, v1, vcc
	v_add_co_u32_e32 v0, vcc, s39, v0
	global_load_dwordx4 v[148:151], v[2:3], off
	global_load_dwordx4 v[152:155], v[4:5], off
	v_addc_co_u32_e32 v1, vcc, 0, v1, vcc
	v_add_co_u32_e32 v2, vcc, s27, v178
	global_load_dwordx4 v[164:167], v176, s[58:59]
	global_load_dwordx4 v[140:143], v176, s[60:61]
	v_addc_co_u32_e32 v3, vcc, 0, v179, vcc
	global_load_dwordx4 v[156:159], v[0:1], off
	global_load_dwordx4 v[160:163], v[2:3], off
	v_add_co_u32_e32 v0, vcc, s34, v178
	v_bfe_u32 v186, v182, 5, 1
	s_nop 0
	v_addc_co_u32_e32 v1, vcc, 0, v179, vcc
	v_add_co_u32_e32 v2, vcc, s35, v178
	s_add_u32 s16, s30, s16
	s_nop 0
	v_addc_co_u32_e32 v3, vcc, 0, v179, vcc
	global_load_dwordx4 v[168:171], v[0:1], off
	global_load_dwordx4 v[172:175], v[2:3], off
	v_and_b32_e32 v0, 0xfffff9f, v182
	v_lshl_or_b32 v2, v185, 6, v184
	v_mul_lo_u32 v3, v0, s40
	v_or_b32_e32 v0, 0x60, v182
	v_lshlrev_b32_e32 v1, 4, v186
	v_mul_lo_u32 v4, v0, s40
	v_mul_u32_u24_e32 v2, 0x90, v2
	s_addc_u32 s17, s31, s17
	v_mov_b32_e32 v0, 0
	v_add_lshl_u32 v189, v7, v6, 1
	v_lshl_add_u64 v[180:181], s[16:17], 0, v[176:177]
	s_mov_b64 s[16:17], 0
	v_add_u32_e32 v188, v1, v3
	v_add_u32_e32 v187, v1, v4
	v_add_u32_e32 v176, v1, v2
	v_mov_b32_e32 v1, v0
	v_mov_b32_e32 v2, v0
	v_mov_b32_e32 v3, v0
	v_mov_b32_e32 v4, v0
	v_mov_b32_e32 v5, v0
	v_mov_b32_e32 v6, v0
	v_mov_b32_e32 v7, v0
	v_mov_b32_e32 v8, v0
	v_mov_b32_e32 v9, v0
	v_mov_b32_e32 v10, v0
	v_mov_b32_e32 v11, v0
	v_mov_b32_e32 v12, v0
	v_mov_b32_e32 v13, v0
	v_mov_b32_e32 v14, v0
	v_mov_b32_e32 v15, v0
	v_mov_b32_e32 v16, v0
	v_mov_b32_e32 v17, v0
	v_mov_b32_e32 v18, v0
	v_mov_b32_e32 v19, v0
	v_mov_b32_e32 v20, v0
	v_mov_b32_e32 v21, v0
	v_mov_b32_e32 v22, v0
	v_mov_b32_e32 v23, v0
	v_mov_b32_e32 v24, v0
	v_mov_b32_e32 v25, v0
	v_mov_b32_e32 v26, v0
	v_mov_b32_e32 v27, v0
	v_mov_b32_e32 v28, v0
	v_mov_b32_e32 v29, v0
	v_mov_b32_e32 v30, v0
	v_mov_b32_e32 v31, v0
	v_mov_b32_e32 v32, v0
	v_mov_b32_e32 v33, v0
	v_mov_b32_e32 v34, v0
	v_mov_b32_e32 v35, v0
	v_mov_b32_e32 v36, v0
	v_mov_b32_e32 v37, v0
	v_mov_b32_e32 v38, v0
	v_mov_b32_e32 v39, v0
	v_mov_b32_e32 v40, v0
	v_mov_b32_e32 v41, v0
	v_mov_b32_e32 v42, v0
	v_mov_b32_e32 v43, v0
	v_mov_b32_e32 v44, v0
	v_mov_b32_e32 v45, v0
	v_mov_b32_e32 v46, v0
	v_mov_b32_e32 v47, v0
	v_mov_b32_e32 v48, v0
	v_mov_b32_e32 v49, v0
	v_mov_b32_e32 v50, v0
	v_mov_b32_e32 v51, v0
	v_mov_b32_e32 v52, v0
	v_mov_b32_e32 v53, v0
	v_mov_b32_e32 v54, v0
	v_mov_b32_e32 v55, v0
	v_mov_b32_e32 v56, v0
	v_mov_b32_e32 v57, v0
	v_mov_b32_e32 v58, v0
	v_mov_b32_e32 v59, v0
	v_mov_b32_e32 v60, v0
	v_mov_b32_e32 v61, v0
	v_mov_b32_e32 v62, v0
	v_mov_b32_e32 v63, v0
	v_mov_b32_e32 v64, v0
	v_mov_b32_e32 v65, v0
	v_mov_b32_e32 v66, v0
	v_mov_b32_e32 v67, v0
	v_mov_b32_e32 v68, v0
	v_mov_b32_e32 v69, v0
	v_mov_b32_e32 v70, v0
	v_mov_b32_e32 v71, v0
	v_mov_b32_e32 v72, v0
	v_mov_b32_e32 v73, v0
	v_mov_b32_e32 v74, v0
	v_mov_b32_e32 v75, v0
	v_mov_b32_e32 v76, v0
	v_mov_b32_e32 v77, v0
	v_mov_b32_e32 v78, v0
	v_mov_b32_e32 v79, v0
	v_mov_b32_e32 v80, v0
	v_mov_b32_e32 v81, v0
	v_mov_b32_e32 v82, v0
	v_mov_b32_e32 v83, v0
	v_mov_b32_e32 v84, v0
	v_mov_b32_e32 v85, v0
	v_mov_b32_e32 v86, v0
	v_mov_b32_e32 v87, v0
	v_mov_b32_e32 v88, v0
	v_mov_b32_e32 v89, v0
	v_mov_b32_e32 v90, v0
	v_mov_b32_e32 v91, v0
	v_mov_b32_e32 v92, v0
	v_mov_b32_e32 v93, v0
	v_mov_b32_e32 v94, v0
	v_mov_b32_e32 v95, v0
	v_mov_b32_e32 v96, v0
	v_mov_b32_e32 v97, v0
	v_mov_b32_e32 v98, v0
	v_mov_b32_e32 v99, v0
	v_mov_b32_e32 v100, v0
	v_mov_b32_e32 v101, v0
	v_mov_b32_e32 v102, v0
	v_mov_b32_e32 v103, v0
	v_mov_b32_e32 v104, v0
	v_mov_b32_e32 v105, v0
	v_mov_b32_e32 v106, v0
	v_mov_b32_e32 v107, v0
	v_mov_b32_e32 v108, v0
	v_mov_b32_e32 v109, v0
	v_mov_b32_e32 v110, v0
	v_mov_b32_e32 v111, v0
	v_mov_b32_e32 v112, v0
	v_mov_b32_e32 v113, v0
	v_mov_b32_e32 v114, v0
	v_mov_b32_e32 v115, v0
	v_mov_b32_e32 v116, v0
	v_mov_b32_e32 v117, v0
	v_mov_b32_e32 v118, v0
	v_mov_b32_e32 v119, v0
	v_mov_b32_e32 v120, v0
	v_mov_b32_e32 v121, v0
	v_mov_b32_e32 v122, v0
	v_mov_b32_e32 v123, v0
	v_mov_b32_e32 v124, v0
	v_mov_b32_e32 v125, v0
	v_mov_b32_e32 v126, v0
	v_mov_b32_e32 v127, v0
	v_readfirstlane_b32 s42, v180
	v_readfirstlane_b32 s43, v181
	v_readfirstlane_b32 s44, v178
	v_readfirstlane_b32 s45, v179
	v_lshrrev_b32_e32 v198, 3, v182
	v_and_b32_e32 v199, 7, v182
	v_lshlrev_b32_e32 v198, 11, v198
	v_lshl_or_b32 v190, v199, 4, v198
	s_lshl_b32 s41, s33, 8
	s_sub_u32 s42, s42, s41
	s_subb_u32 s43, s43, 0
	s_sub_u32 s44, s44, s41
	s_subb_u32 s45, s45, 0
	s_add_u32 s42, s42, 0x2957980
	s_addc_u32 s43, s43, 0
	s_add_u32 s44, s44, 0x80
	s_addc_u32 s45, s45, 0
	v_add_u32_e32 v191, 0x10000, v190
	v_add_u32_e32 v192, 0x20000, v190
	v_add_u32_e32 v193, 0x30000, v190
	v_add_u32_e32 v194, 0x40000, v190
	v_add_u32_e32 v195, 0x50000, v190
	v_add_u32_e32 v196, 0x60000, v190
	v_add_u32_e32 v197, 0x70000, v190
	s_waitcnt lgkmcnt(0)
	s_barrier
	s_waitcnt vmcnt(0)
	ds_write_b128 v189, v[164:167]
	ds_write_b128 v189, v[128:131] offset:4608
	ds_write_b128 v189, v[132:135] offset:9216
	ds_write_b128 v189, v[136:139] offset:13824
	ds_write_b128 v189, v[144:147] offset:18432
	ds_write_b128 v189, v[148:151] offset:23040
	ds_write_b128 v189, v[152:155] offset:27648
	ds_write_b128 v189, v[156:159] offset:32256
	ds_write_b128 v189, v[140:143] offset:36864
	ds_write_b128 v189, v[160:163] offset:41472
	ds_write_b128 v189, v[168:171] offset:46080
	ds_write_b128 v189, v[172:175] offset:50688
	global_load_dwordx4 v[164:167], v190, s[42:43]
	global_load_dwordx4 v[128:131], v191, s[42:43]
	global_load_dwordx4 v[132:135], v192, s[42:43]
	global_load_dwordx4 v[136:139], v193, s[42:43]
	global_load_dwordx4 v[144:147], v194, s[42:43]
	global_load_dwordx4 v[148:151], v195, s[42:43]
	global_load_dwordx4 v[152:155], v196, s[42:43]
	global_load_dwordx4 v[156:159], v197, s[42:43]
	s_waitcnt lgkmcnt(0)
	s_barrier
.LBB0_1284:
	ds_read_b128 v[216:219], v176 offset:36864
	ds_read_b128 v[200:203], v188
	ds_read_b128 v[220:223], v176 offset:41472
	ds_read_b128 v[204:207], v188 offset:4608
	ds_read_b128 v[208:211], v188 offset:9216
	ds_read_b128 v[212:215], v187
	s_waitcnt lgkmcnt(4)
	v_mfma_f32_32x32x16_bf16 v[112:127], v[200:203], v[216:219], v[112:127]
	ds_read_b128 v[240:243], v176 offset:36896
	global_load_dwordx4 v[140:143], v190, s[44:45]
	s_waitcnt lgkmcnt(4)
	v_mfma_f32_32x32x16_bf16 v[96:111], v[200:203], v[220:223], v[96:111]
	ds_read_b128 v[224:227], v188 offset:32
	global_load_dwordx4 v[160:163], v191, s[44:45]
	s_waitcnt lgkmcnt(4)
	v_mfma_f32_32x32x16_bf16 v[80:95], v[204:207], v[216:219], v[80:95]
	ds_read_b128 v[244:247], v176 offset:41504
	global_load_dwordx4 v[168:171], v192, s[44:45]
	s_waitcnt lgkmcnt(5)
	v_mfma_f32_32x32x16_bf16 v[64:79], v[204:207], v[220:223], v[64:79]
	ds_read_b128 v[228:231], v188 offset:4640
	global_load_dwordx4 v[172:175], v193, s[44:45]
	s_add_u32 s42, s42, 0x80
	s_addc_u32 s43, s43, 0
	s_add_u32 s44, s44, 0x80
	s_addc_u32 s45, s45, 0
	s_add_u32 s16, s16, 0x80
	s_waitcnt lgkmcnt(5)
	v_mfma_f32_32x32x16_bf16 v[48:63], v[208:211], v[216:219], v[48:63]
	ds_read_b128 v[232:235], v188 offset:9248
	s_waitcnt lgkmcnt(6)
	v_mfma_f32_32x32x16_bf16 v[32:47], v[208:211], v[220:223], v[32:47]
	ds_read_b128 v[236:239], v187 offset:32
	s_waitcnt lgkmcnt(6)
	v_mfma_f32_32x32x16_bf16 v[16:31], v[212:215], v[216:219], v[16:31]
	s_waitcnt lgkmcnt(6)
	v_mfma_f32_32x32x16_bf16 v[0:15], v[212:215], v[220:223], v[0:15]
	s_waitcnt lgkmcnt(4)
	v_mfma_f32_32x32x16_bf16 v[112:127], v[224:227], v[240:243], v[112:127]
	ds_read_b128 v[200:203], v188 offset:64
	s_waitcnt lgkmcnt(4)
	v_mfma_f32_32x32x16_bf16 v[96:111], v[224:227], v[244:247], v[96:111]
	ds_read_b128 v[204:207], v188 offset:4672
	s_waitcnt lgkmcnt(4)
	v_mfma_f32_32x32x16_bf16 v[80:95], v[228:231], v[240:243], v[80:95]
	ds_read_b128 v[208:211], v188 offset:9280
	s_waitcnt lgkmcnt(5)
	v_mfma_f32_32x32x16_bf16 v[64:79], v[228:231], v[244:247], v[64:79]
	ds_read_b128 v[212:215], v187 offset:64
	s_waitcnt lgkmcnt(5)
	v_mfma_f32_32x32x16_bf16 v[48:63], v[232:235], v[240:243], v[48:63]
	ds_read_b128 v[216:219], v176 offset:36928
	s_waitcnt lgkmcnt(6)
	v_mfma_f32_32x32x16_bf16 v[32:47], v[232:235], v[244:247], v[32:47]
	ds_read_b128 v[220:223], v176 offset:41536
	s_waitcnt lgkmcnt(6)
	v_mfma_f32_32x32x16_bf16 v[16:31], v[236:239], v[240:243], v[16:31]
	s_waitcnt lgkmcnt(6)
	v_mfma_f32_32x32x16_bf16 v[0:15], v[236:239], v[244:247], v[0:15]
	s_waitcnt lgkmcnt(1)
	v_mfma_f32_32x32x16_bf16 v[112:127], v[200:203], v[216:219], v[112:127]
	ds_read_b128 v[224:227], v188 offset:96
	s_waitcnt lgkmcnt(1)
	v_mfma_f32_32x32x16_bf16 v[96:111], v[200:203], v[220:223], v[96:111]
	ds_read_b128 v[228:231], v188 offset:4704
	s_waitcnt lgkmcnt(3)
	v_mfma_f32_32x32x16_bf16 v[80:95], v[204:207], v[216:219], v[80:95]
	ds_read_b128 v[232:235], v188 offset:9312
	s_waitcnt lgkmcnt(3)
	v_mfma_f32_32x32x16_bf16 v[64:79], v[204:207], v[220:223], v[64:79]
	ds_read_b128 v[236:239], v187 offset:96
	s_waitcnt lgkmcnt(5)
	v_mfma_f32_32x32x16_bf16 v[48:63], v[208:211], v[216:219], v[48:63]
	ds_read_b128 v[240:243], v176 offset:36960
	s_waitcnt lgkmcnt(5)
	v_mfma_f32_32x32x16_bf16 v[32:47], v[208:211], v[220:223], v[32:47]
	ds_read_b128 v[244:247], v176 offset:41568
	s_waitcnt lgkmcnt(7)
	v_mfma_f32_32x32x16_bf16 v[16:31], v[212:215], v[216:219], v[16:31]
	s_waitcnt lgkmcnt(6)
	v_mfma_f32_32x32x16_bf16 v[0:15], v[212:215], v[220:223], v[0:15]
	s_waitcnt lgkmcnt(0)
	s_barrier
	s_waitcnt vmcnt(4)
	s_waitcnt lgkmcnt(1)
	v_mfma_f32_32x32x16_bf16 v[112:127], v[224:227], v[240:243], v[112:127]
	ds_write_b128 v189, v[164:167]
	ds_write_b128 v189, v[128:131] offset:4608
	s_waitcnt lgkmcnt(2)
	v_mfma_f32_32x32x16_bf16 v[96:111], v[224:227], v[244:247], v[96:111]
	ds_write_b128 v189, v[132:135] offset:9216
	global_load_dwordx4 v[164:167], v190, s[42:43]
	s_waitcnt lgkmcnt(4)
	v_mfma_f32_32x32x16_bf16 v[80:95], v[228:231], v[240:243], v[80:95]
	ds_write_b128 v189, v[136:139] offset:13824
	ds_write_b128 v189, v[144:147] offset:18432
	global_load_dwordx4 v[128:131], v191, s[42:43]
	s_waitcnt lgkmcnt(5)
	v_mfma_f32_32x32x16_bf16 v[64:79], v[228:231], v[244:247], v[64:79]
	ds_write_b128 v189, v[148:151] offset:23040
	global_load_dwordx4 v[132:135], v192, s[42:43]
	s_waitcnt lgkmcnt(7)
	v_mfma_f32_32x32x16_bf16 v[48:63], v[232:235], v[240:243], v[48:63]
	ds_write_b128 v189, v[152:155] offset:27648
	ds_write_b128 v189, v[156:159] offset:32256
	global_load_dwordx4 v[136:139], v193, s[42:43]
	s_waitcnt lgkmcnt(8)
	v_mfma_f32_32x32x16_bf16 v[32:47], v[232:235], v[244:247], v[32:47]
	s_waitcnt vmcnt(4)
	ds_write_b128 v189, v[140:143] offset:36864
	global_load_dwordx4 v[144:147], v194, s[42:43]
	s_waitcnt lgkmcnt(10)
	v_mfma_f32_32x32x16_bf16 v[16:31], v[236:239], v[240:243], v[16:31]
	ds_write_b128 v189, v[160:163] offset:41472
	ds_write_b128 v189, v[168:171] offset:46080
	global_load_dwordx4 v[148:151], v195, s[42:43]
	s_waitcnt lgkmcnt(11)
	v_mfma_f32_32x32x16_bf16 v[0:15], v[236:239], v[244:247], v[0:15]
	ds_write_b128 v189, v[172:175] offset:50688
	global_load_dwordx4 v[152:155], v196, s[42:43]
	global_load_dwordx4 v[156:159], v197, s[42:43]
	s_waitcnt lgkmcnt(0)
	s_barrier
	s_cmpk_lg_i32 s16, 0x780
	s_cbranch_scc1 .LBB0_1284
	ds_read_b128 v[216:219], v176 offset:36864
	ds_read_b128 v[200:203], v188
	ds_read_b128 v[220:223], v176 offset:41472
	ds_read_b128 v[204:207], v188 offset:4608
	ds_read_b128 v[208:211], v188 offset:9216
	ds_read_b128 v[212:215], v187
	s_waitcnt lgkmcnt(4)
	v_mfma_f32_32x32x16_bf16 v[112:127], v[200:203], v[216:219], v[112:127]
	ds_read_b128 v[240:243], v176 offset:36896
	s_waitcnt lgkmcnt(4)
	v_mfma_f32_32x32x16_bf16 v[96:111], v[200:203], v[220:223], v[96:111]
	ds_read_b128 v[224:227], v188 offset:32
	s_waitcnt lgkmcnt(4)
	v_mfma_f32_32x32x16_bf16 v[80:95], v[204:207], v[216:219], v[80:95]
	ds_read_b128 v[244:247], v176 offset:41504
	s_waitcnt lgkmcnt(5)
	v_mfma_f32_32x32x16_bf16 v[64:79], v[204:207], v[220:223], v[64:79]
	ds_read_b128 v[228:231], v188 offset:4640
	s_waitcnt lgkmcnt(5)
	v_mfma_f32_32x32x16_bf16 v[48:63], v[208:211], v[216:219], v[48:63]
	ds_read_b128 v[232:235], v188 offset:9248
	s_waitcnt lgkmcnt(6)
	v_mfma_f32_32x32x16_bf16 v[32:47], v[208:211], v[220:223], v[32:47]
	ds_read_b128 v[236:239], v187 offset:32
	s_waitcnt lgkmcnt(6)
	v_mfma_f32_32x32x16_bf16 v[16:31], v[212:215], v[216:219], v[16:31]
	s_waitcnt lgkmcnt(6)
	v_mfma_f32_32x32x16_bf16 v[0:15], v[212:215], v[220:223], v[0:15]
	s_waitcnt lgkmcnt(4)
	v_mfma_f32_32x32x16_bf16 v[112:127], v[224:227], v[240:243], v[112:127]
	ds_read_b128 v[200:203], v188 offset:64
	s_waitcnt lgkmcnt(4)
	v_mfma_f32_32x32x16_bf16 v[96:111], v[224:227], v[244:247], v[96:111]
	ds_read_b128 v[204:207], v188 offset:4672
	s_waitcnt lgkmcnt(4)
	v_mfma_f32_32x32x16_bf16 v[80:95], v[228:231], v[240:243], v[80:95]
	ds_read_b128 v[208:211], v188 offset:9280
	s_waitcnt lgkmcnt(5)
	v_mfma_f32_32x32x16_bf16 v[64:79], v[228:231], v[244:247], v[64:79]
	ds_read_b128 v[212:215], v187 offset:64
	s_waitcnt lgkmcnt(5)
	v_mfma_f32_32x32x16_bf16 v[48:63], v[232:235], v[240:243], v[48:63]
	ds_read_b128 v[216:219], v176 offset:36928
	s_waitcnt lgkmcnt(6)
	v_mfma_f32_32x32x16_bf16 v[32:47], v[232:235], v[244:247], v[32:47]
	ds_read_b128 v[220:223], v176 offset:41536
	s_waitcnt lgkmcnt(6)
	v_mfma_f32_32x32x16_bf16 v[16:31], v[236:239], v[240:243], v[16:31]
	s_waitcnt lgkmcnt(6)
	v_mfma_f32_32x32x16_bf16 v[0:15], v[236:239], v[244:247], v[0:15]
	s_waitcnt lgkmcnt(1)
	v_mfma_f32_32x32x16_bf16 v[112:127], v[200:203], v[216:219], v[112:127]
	ds_read_b128 v[224:227], v188 offset:96
	s_waitcnt lgkmcnt(1)
	v_mfma_f32_32x32x16_bf16 v[96:111], v[200:203], v[220:223], v[96:111]
	ds_read_b128 v[228:231], v188 offset:4704
	s_waitcnt lgkmcnt(3)
	v_mfma_f32_32x32x16_bf16 v[80:95], v[204:207], v[216:219], v[80:95]
	ds_read_b128 v[232:235], v188 offset:9312
	s_waitcnt lgkmcnt(3)
	v_mfma_f32_32x32x16_bf16 v[64:79], v[204:207], v[220:223], v[64:79]
	ds_read_b128 v[236:239], v187 offset:96
	s_waitcnt lgkmcnt(5)
	v_mfma_f32_32x32x16_bf16 v[48:63], v[208:211], v[216:219], v[48:63]
	ds_read_b128 v[240:243], v176 offset:36960
	s_waitcnt lgkmcnt(5)
	v_mfma_f32_32x32x16_bf16 v[32:47], v[208:211], v[220:223], v[32:47]
	ds_read_b128 v[244:247], v176 offset:41568
	s_waitcnt lgkmcnt(7)
	v_mfma_f32_32x32x16_bf16 v[16:31], v[212:215], v[216:219], v[16:31]
	s_waitcnt lgkmcnt(6)
	v_mfma_f32_32x32x16_bf16 v[0:15], v[212:215], v[220:223], v[0:15]
	s_waitcnt lgkmcnt(1)
	v_mfma_f32_32x32x16_bf16 v[112:127], v[224:227], v[240:243], v[112:127]
	s_waitcnt lgkmcnt(0)
	v_mfma_f32_32x32x16_bf16 v[96:111], v[224:227], v[244:247], v[96:111]
	s_waitcnt lgkmcnt(1)
	v_mfma_f32_32x32x16_bf16 v[80:95], v[228:231], v[240:243], v[80:95]
	s_waitcnt lgkmcnt(0)
	v_mfma_f32_32x32x16_bf16 v[64:79], v[228:231], v[244:247], v[64:79]
	s_waitcnt lgkmcnt(1)
	v_mfma_f32_32x32x16_bf16 v[48:63], v[232:235], v[240:243], v[48:63]
	s_waitcnt lgkmcnt(0)
	v_mfma_f32_32x32x16_bf16 v[32:47], v[232:235], v[244:247], v[32:47]
	s_waitcnt lgkmcnt(1)
	v_mfma_f32_32x32x16_bf16 v[16:31], v[236:239], v[240:243], v[16:31]
	s_waitcnt lgkmcnt(0)
	v_mfma_f32_32x32x16_bf16 v[0:15], v[236:239], v[244:247], v[0:15]
	s_waitcnt vmcnt(0)
	s_mul_i32 s41, s12, 0x1240
	s_add_u32 s42, s30, s41
	s_addc_u32 s43, s31, 0
	s_lshl_b32 s41, s8, 1
	s_add_u32 s42, s42, s41
	s_addc_u32 s43, s43, 0
	s_add_u32 s42, s42, 0x7157900
	s_addc_u32 s43, s43, 0
	v_and_b32_e32 v131, 15, v182
	v_lshrrev_b32_e32 v172, 4, v182
	v_lshl_add_u32 v130, v131, 3, s8
	s_movk_i32 s41, 0x920
	v_cmp_gt_u32_e64 s[44:45], s41, v130
	v_mul_u32_u24_e32 v164, 0x1240, v172
	v_lshl_add_u32 v164, v131, 4, v164
	v_add_u32_e32 v165, 0x12400, v164
	v_add_u32_e32 v166, 0x24800, v164
	v_add_u32_e32 v167, 0x36c00, v164
	v_add_u32_e32 v168, 0x92000, v164
	v_add_u32_e32 v169, 0xa4400, v164
	v_add_u32_e32 v170, 0xb6800, v164
	v_add_u32_e32 v171, 0xc8c00, v164
	v_mul_u32_u24_e32 v129, 0x110, v172
	v_lshl_add_u32 v129, v131, 4, v129
	v_lshrrev_b32_e32 v131, 7, v182
	v_bfe_u32 v172, v182, 5, 1
	v_lshlrev_b32_e32 v131, 6, v131
	v_lshl_or_b32 v131, v172, 2, v131
	v_mul_u32_u24_e32 v131, 136, v131
	v_and_b32_e32 v172, 0x5f, v182
	v_add_lshl_u32 v128, v131, v172, 1
	s_barrier
	v_cvt_pk_bf16_f32 v112, v112, v113
	v_cvt_pk_bf16_f32 v114, v114, v115
	v_cvt_pk_bf16_f32 v116, v116, v117
	v_cvt_pk_bf16_f32 v118, v118, v119
	v_cvt_pk_bf16_f32 v120, v120, v121
	v_cvt_pk_bf16_f32 v122, v122, v123
	v_cvt_pk_bf16_f32 v124, v124, v125
	v_cvt_pk_bf16_f32 v126, v126, v127
	v_cvt_pk_bf16_f32 v96, v96, v97
	v_cvt_pk_bf16_f32 v98, v98, v99
	v_cvt_pk_bf16_f32 v100, v100, v101
	v_cvt_pk_bf16_f32 v102, v102, v103
	v_cvt_pk_bf16_f32 v104, v104, v105
	v_cvt_pk_bf16_f32 v106, v106, v107
	v_cvt_pk_bf16_f32 v108, v108, v109
	v_cvt_pk_bf16_f32 v110, v110, v111
	v_cvt_pk_bf16_f32 v80, v80, v81
	v_cvt_pk_bf16_f32 v82, v82, v83
	v_cvt_pk_bf16_f32 v84, v84, v85
	v_cvt_pk_bf16_f32 v86, v86, v87
	v_cvt_pk_bf16_f32 v88, v88, v89
	v_cvt_pk_bf16_f32 v90, v90, v91
	v_cvt_pk_bf16_f32 v92, v92, v93
	v_cvt_pk_bf16_f32 v94, v94, v95
	v_cvt_pk_bf16_f32 v64, v64, v65
	v_cvt_pk_bf16_f32 v66, v66, v67
	v_cvt_pk_bf16_f32 v68, v68, v69
	v_cvt_pk_bf16_f32 v70, v70, v71
	v_cvt_pk_bf16_f32 v72, v72, v73
	v_cvt_pk_bf16_f32 v74, v74, v75
	v_cvt_pk_bf16_f32 v76, v76, v77
	v_cvt_pk_bf16_f32 v78, v78, v79
	ds_write_b16 v128, v112
	ds_write_b16_d16_hi v128, v112 offset:272
	ds_write_b16 v128, v114 offset:544
	ds_write_b16_d16_hi v128, v114 offset:816
	ds_write_b16 v128, v116 offset:2176
	ds_write_b16_d16_hi v128, v116 offset:2448
	ds_write_b16 v128, v118 offset:2720
	ds_write_b16_d16_hi v128, v118 offset:2992
	ds_write_b16 v128, v120 offset:4352
	ds_write_b16_d16_hi v128, v120 offset:4624
	ds_write_b16 v128, v122 offset:4896
	ds_write_b16_d16_hi v128, v122 offset:5168
	ds_write_b16 v128, v124 offset:6528
	ds_write_b16_d16_hi v128, v124 offset:6800
	ds_write_b16 v128, v126 offset:7072
	ds_write_b16_d16_hi v128, v126 offset:7344
	ds_write_b16 v128, v96 offset:64
	ds_write_b16_d16_hi v128, v96 offset:336
	ds_write_b16 v128, v98 offset:608
	ds_write_b16_d16_hi v128, v98 offset:880
	ds_write_b16 v128, v100 offset:2240
	ds_write_b16_d16_hi v128, v100 offset:2512
	ds_write_b16 v128, v102 offset:2784
	ds_write_b16_d16_hi v128, v102 offset:3056
	ds_write_b16 v128, v104 offset:4416
	ds_write_b16_d16_hi v128, v104 offset:4688
	ds_write_b16 v128, v106 offset:4960
	ds_write_b16_d16_hi v128, v106 offset:5232
	ds_write_b16 v128, v108 offset:6592
	ds_write_b16_d16_hi v128, v108 offset:6864
	ds_write_b16 v128, v110 offset:7136
	ds_write_b16_d16_hi v128, v110 offset:7408
	ds_write_b16 v128, v80 offset:8704
	ds_write_b16_d16_hi v128, v80 offset:8976
	ds_write_b16 v128, v82 offset:9248
	ds_write_b16_d16_hi v128, v82 offset:9520
	ds_write_b16 v128, v84 offset:10880
	ds_write_b16_d16_hi v128, v84 offset:11152
	ds_write_b16 v128, v86 offset:11424
	ds_write_b16_d16_hi v128, v86 offset:11696
	ds_write_b16 v128, v88 offset:13056
	ds_write_b16_d16_hi v128, v88 offset:13328
	ds_write_b16 v128, v90 offset:13600
	ds_write_b16_d16_hi v128, v90 offset:13872
	ds_write_b16 v128, v92 offset:15232
	ds_write_b16_d16_hi v128, v92 offset:15504
	ds_write_b16 v128, v94 offset:15776
	ds_write_b16_d16_hi v128, v94 offset:16048
	ds_write_b16 v128, v64 offset:8768
	ds_write_b16_d16_hi v128, v64 offset:9040
	ds_write_b16 v128, v66 offset:9312
	ds_write_b16_d16_hi v128, v66 offset:9584
	ds_write_b16 v128, v68 offset:10944
	ds_write_b16_d16_hi v128, v68 offset:11216
	ds_write_b16 v128, v70 offset:11488
	ds_write_b16_d16_hi v128, v70 offset:11760
	ds_write_b16 v128, v72 offset:13120
	ds_write_b16_d16_hi v128, v72 offset:13392
	ds_write_b16 v128, v74 offset:13664
	ds_write_b16_d16_hi v128, v74 offset:13936
	ds_write_b16 v128, v76 offset:15296
	ds_write_b16_d16_hi v128, v76 offset:15568
	ds_write_b16 v128, v78 offset:15840
	ds_write_b16_d16_hi v128, v78 offset:16112
	s_waitcnt lgkmcnt(0)
	s_barrier
	ds_read_b128 v[132:135], v129
	ds_read_b128 v[136:139], v129 offset:4352
	ds_read_b128 v[140:143], v129 offset:8704
	ds_read_b128 v[144:147], v129 offset:13056
	ds_read_b128 v[148:151], v129 offset:17408
	ds_read_b128 v[152:155], v129 offset:21760
	ds_read_b128 v[156:159], v129 offset:26112
	ds_read_b128 v[160:163], v129 offset:30464
	v_cvt_pk_bf16_f32 v48, v48, v49
	v_cvt_pk_bf16_f32 v50, v50, v51
	v_cvt_pk_bf16_f32 v52, v52, v53
	v_cvt_pk_bf16_f32 v54, v54, v55
	v_cvt_pk_bf16_f32 v56, v56, v57
	v_cvt_pk_bf16_f32 v58, v58, v59
	v_cvt_pk_bf16_f32 v60, v60, v61
	v_cvt_pk_bf16_f32 v62, v62, v63
	v_cvt_pk_bf16_f32 v32, v32, v33
	v_cvt_pk_bf16_f32 v34, v34, v35
	v_cvt_pk_bf16_f32 v36, v36, v37
	v_cvt_pk_bf16_f32 v38, v38, v39
	v_cvt_pk_bf16_f32 v40, v40, v41
	v_cvt_pk_bf16_f32 v42, v42, v43
	v_cvt_pk_bf16_f32 v44, v44, v45
	v_cvt_pk_bf16_f32 v46, v46, v47
	v_cvt_pk_bf16_f32 v16, v16, v17
	v_cvt_pk_bf16_f32 v18, v18, v19
	v_cvt_pk_bf16_f32 v20, v20, v21
	v_cvt_pk_bf16_f32 v22, v22, v23
	v_cvt_pk_bf16_f32 v24, v24, v25
	v_cvt_pk_bf16_f32 v26, v26, v27
	v_cvt_pk_bf16_f32 v28, v28, v29
	v_cvt_pk_bf16_f32 v30, v30, v31
	v_cvt_pk_bf16_f32 v0, v0, v1
	v_cvt_pk_bf16_f32 v2, v2, v3
	v_cvt_pk_bf16_f32 v4, v4, v5
	v_cvt_pk_bf16_f32 v6, v6, v7
	v_cvt_pk_bf16_f32 v8, v8, v9
	v_cvt_pk_bf16_f32 v10, v10, v11
	v_cvt_pk_bf16_f32 v12, v12, v13
	v_cvt_pk_bf16_f32 v14, v14, v15
	s_and_saveexec_b64 s[46:47], s[44:45]
	s_waitcnt lgkmcnt(7)
	global_store_dwordx4 v164, v[132:135], s[42:43]
	s_waitcnt lgkmcnt(6)
	global_store_dwordx4 v165, v[136:139], s[42:43]
	s_waitcnt lgkmcnt(5)
	global_store_dwordx4 v166, v[140:143], s[42:43]
	s_waitcnt lgkmcnt(4)
	global_store_dwordx4 v167, v[144:147], s[42:43]
	s_waitcnt lgkmcnt(3)
	global_store_dwordx4 v168, v[148:151], s[42:43]
	s_waitcnt lgkmcnt(2)
	global_store_dwordx4 v169, v[152:155], s[42:43]
	s_waitcnt lgkmcnt(1)
	global_store_dwordx4 v170, v[156:159], s[42:43]
	s_waitcnt lgkmcnt(0)
	global_store_dwordx4 v171, v[160:163], s[42:43]
	s_or_b64 exec, exec, s[46:47]
	s_barrier
	ds_write_b16 v128, v48
	ds_write_b16_d16_hi v128, v48 offset:272
	ds_write_b16 v128, v50 offset:544
	ds_write_b16_d16_hi v128, v50 offset:816
	ds_write_b16 v128, v52 offset:2176
	ds_write_b16_d16_hi v128, v52 offset:2448
	ds_write_b16 v128, v54 offset:2720
	ds_write_b16_d16_hi v128, v54 offset:2992
	ds_write_b16 v128, v56 offset:4352
	ds_write_b16_d16_hi v128, v56 offset:4624
	ds_write_b16 v128, v58 offset:4896
	ds_write_b16_d16_hi v128, v58 offset:5168
	ds_write_b16 v128, v60 offset:6528
	ds_write_b16_d16_hi v128, v60 offset:6800
	ds_write_b16 v128, v62 offset:7072
	ds_write_b16_d16_hi v128, v62 offset:7344
	ds_write_b16 v128, v32 offset:64
	ds_write_b16_d16_hi v128, v32 offset:336
	ds_write_b16 v128, v34 offset:608
	ds_write_b16_d16_hi v128, v34 offset:880
	ds_write_b16 v128, v36 offset:2240
	ds_write_b16_d16_hi v128, v36 offset:2512
	ds_write_b16 v128, v38 offset:2784
	ds_write_b16_d16_hi v128, v38 offset:3056
	ds_write_b16 v128, v40 offset:4416
	ds_write_b16_d16_hi v128, v40 offset:4688
	ds_write_b16 v128, v42 offset:4960
	ds_write_b16_d16_hi v128, v42 offset:5232
	ds_write_b16 v128, v44 offset:6592
	ds_write_b16_d16_hi v128, v44 offset:6864
	ds_write_b16 v128, v46 offset:7136
	ds_write_b16_d16_hi v128, v46 offset:7408
	ds_write_b16 v128, v16 offset:8704
	ds_write_b16_d16_hi v128, v16 offset:8976
	ds_write_b16 v128, v18 offset:9248
	ds_write_b16_d16_hi v128, v18 offset:9520
	ds_write_b16 v128, v20 offset:10880
	ds_write_b16_d16_hi v128, v20 offset:11152
	ds_write_b16 v128, v22 offset:11424
	ds_write_b16_d16_hi v128, v22 offset:11696
	ds_write_b16 v128, v24 offset:13056
	ds_write_b16_d16_hi v128, v24 offset:13328
	ds_write_b16 v128, v26 offset:13600
	ds_write_b16_d16_hi v128, v26 offset:13872
	ds_write_b16 v128, v28 offset:15232
	ds_write_b16_d16_hi v128, v28 offset:15504
	ds_write_b16 v128, v30 offset:15776
	ds_write_b16_d16_hi v128, v30 offset:16048
	ds_write_b16 v128, v0 offset:8768
	ds_write_b16_d16_hi v128, v0 offset:9040
	ds_write_b16 v128, v2 offset:9312
	ds_write_b16_d16_hi v128, v2 offset:9584
	ds_write_b16 v128, v4 offset:10944
	ds_write_b16_d16_hi v128, v4 offset:11216
	ds_write_b16 v128, v6 offset:11488
	ds_write_b16_d16_hi v128, v6 offset:11760
	ds_write_b16 v128, v8 offset:13120
	ds_write_b16_d16_hi v128, v8 offset:13392
	ds_write_b16 v128, v10 offset:13664
	ds_write_b16_d16_hi v128, v10 offset:13936
	ds_write_b16 v128, v12 offset:15296
	ds_write_b16_d16_hi v128, v12 offset:15568
	ds_write_b16 v128, v14 offset:15840
	ds_write_b16_d16_hi v128, v14 offset:16112
	s_waitcnt lgkmcnt(0)
	s_barrier
	ds_read_b128 v[132:135], v129
	ds_read_b128 v[136:139], v129 offset:4352
	ds_read_b128 v[140:143], v129 offset:8704
	ds_read_b128 v[144:147], v129 offset:13056
	ds_read_b128 v[148:151], v129 offset:17408
	ds_read_b128 v[152:155], v129 offset:21760
	ds_read_b128 v[156:159], v129 offset:26112
	ds_read_b128 v[160:163], v129 offset:30464
	v_add_u32_e32 v164, 0x49000, v164
	v_add_u32_e32 v165, 0x49000, v165
	v_add_u32_e32 v166, 0x49000, v166
	v_add_u32_e32 v167, 0x49000, v167
	v_add_u32_e32 v168, 0x49000, v168
	v_add_u32_e32 v169, 0x49000, v169
	v_add_u32_e32 v170, 0x49000, v170
	v_add_u32_e32 v171, 0x49000, v171
	s_and_saveexec_b64 s[46:47], s[44:45]
	s_waitcnt lgkmcnt(7)
	global_store_dwordx4 v164, v[132:135], s[42:43]
	s_waitcnt lgkmcnt(6)
	global_store_dwordx4 v165, v[136:139], s[42:43]
	s_waitcnt lgkmcnt(5)
	global_store_dwordx4 v166, v[140:143], s[42:43]
	s_waitcnt lgkmcnt(4)
	global_store_dwordx4 v167, v[144:147], s[42:43]
	s_waitcnt lgkmcnt(3)
	global_store_dwordx4 v168, v[148:151], s[42:43]
	s_waitcnt lgkmcnt(2)
	global_store_dwordx4 v169, v[152:155], s[42:43]
	s_waitcnt lgkmcnt(1)
	global_store_dwordx4 v170, v[156:159], s[42:43]
	s_waitcnt lgkmcnt(0)
	global_store_dwordx4 v171, v[160:163], s[42:43]
	s_or_b64 exec, exec, s[46:47]
	s_branch .LBB0_1281

.LBB0_1977:
	ds_read_b128 v[216:219], v188 offset:36864
	ds_read_b128 v[200:203], v187
	ds_read_b128 v[220:223], v188 offset:41472
	ds_read_b128 v[204:207], v187 offset:4608
	ds_read_b128 v[208:211], v187 offset:9216
	ds_read_b128 v[212:215], v176
	s_waitcnt lgkmcnt(4)
	v_mfma_f32_32x32x16_bf16 v[112:127], v[200:203], v[216:219], v[112:127]
	ds_read_b128 v[240:243], v188 offset:36896
	global_load_dwordx4 v[152:155], v190, s[40:41]
	s_waitcnt lgkmcnt(4)
	v_mfma_f32_32x32x16_bf16 v[96:111], v[200:203], v[220:223], v[96:111]
	ds_read_b128 v[224:227], v187 offset:32
	global_load_dwordx4 v[164:167], v191, s[40:41]
	s_waitcnt lgkmcnt(4)
	v_mfma_f32_32x32x16_bf16 v[80:95], v[204:207], v[216:219], v[80:95]
	ds_read_b128 v[244:247], v188 offset:41504
	global_load_dwordx4 v[168:171], v192, s[40:41]
	s_waitcnt lgkmcnt(5)
	v_mfma_f32_32x32x16_bf16 v[64:79], v[204:207], v[220:223], v[64:79]
	ds_read_b128 v[228:231], v187 offset:4640
	global_load_dwordx4 v[172:175], v193, s[40:41]
	s_add_u32 s38, s38, 0x80
	s_addc_u32 s39, s39, 0
	s_add_u32 s40, s40, 0x80
	s_addc_u32 s41, s41, 0
	s_add_u32 s12, s12, 0x80
	s_waitcnt lgkmcnt(5)
	v_mfma_f32_32x32x16_bf16 v[48:63], v[208:211], v[216:219], v[48:63]
	ds_read_b128 v[232:235], v187 offset:9248
	s_waitcnt lgkmcnt(6)
	v_mfma_f32_32x32x16_bf16 v[32:47], v[208:211], v[220:223], v[32:47]
	ds_read_b128 v[236:239], v176 offset:32
	s_waitcnt lgkmcnt(6)
	v_mfma_f32_32x32x16_bf16 v[16:31], v[212:215], v[216:219], v[16:31]
	s_waitcnt lgkmcnt(6)
	v_mfma_f32_32x32x16_bf16 v[0:15], v[212:215], v[220:223], v[0:15]
	s_waitcnt lgkmcnt(4)
	v_mfma_f32_32x32x16_bf16 v[112:127], v[224:227], v[240:243], v[112:127]
	ds_read_b128 v[200:203], v187 offset:64
	s_waitcnt lgkmcnt(4)
	v_mfma_f32_32x32x16_bf16 v[96:111], v[224:227], v[244:247], v[96:111]
	ds_read_b128 v[204:207], v187 offset:4672
	s_waitcnt lgkmcnt(4)
	v_mfma_f32_32x32x16_bf16 v[80:95], v[228:231], v[240:243], v[80:95]
	ds_read_b128 v[208:211], v187 offset:9280
	s_waitcnt lgkmcnt(5)
	v_mfma_f32_32x32x16_bf16 v[64:79], v[228:231], v[244:247], v[64:79]
	ds_read_b128 v[212:215], v176 offset:64
	s_waitcnt lgkmcnt(5)
	v_mfma_f32_32x32x16_bf16 v[48:63], v[232:235], v[240:243], v[48:63]
	ds_read_b128 v[216:219], v188 offset:36928
	s_waitcnt lgkmcnt(6)
	v_mfma_f32_32x32x16_bf16 v[32:47], v[232:235], v[244:247], v[32:47]
	ds_read_b128 v[220:223], v188 offset:41536
	s_waitcnt lgkmcnt(6)
	v_mfma_f32_32x32x16_bf16 v[16:31], v[236:239], v[240:243], v[16:31]
	s_waitcnt lgkmcnt(6)
	v_mfma_f32_32x32x16_bf16 v[0:15], v[236:239], v[244:247], v[0:15]
	s_waitcnt lgkmcnt(1)
	v_mfma_f32_32x32x16_bf16 v[112:127], v[200:203], v[216:219], v[112:127]
	ds_read_b128 v[224:227], v187 offset:96
	s_waitcnt lgkmcnt(1)
	v_mfma_f32_32x32x16_bf16 v[96:111], v[200:203], v[220:223], v[96:111]
	ds_read_b128 v[228:231], v187 offset:4704
	s_waitcnt lgkmcnt(3)
	v_mfma_f32_32x32x16_bf16 v[80:95], v[204:207], v[216:219], v[80:95]
	ds_read_b128 v[232:235], v187 offset:9312
	s_waitcnt lgkmcnt(3)
	v_mfma_f32_32x32x16_bf16 v[64:79], v[204:207], v[220:223], v[64:79]
	ds_read_b128 v[236:239], v176 offset:96
	s_waitcnt lgkmcnt(5)
	v_mfma_f32_32x32x16_bf16 v[48:63], v[208:211], v[216:219], v[48:63]
	ds_read_b128 v[240:243], v188 offset:36960
	s_waitcnt lgkmcnt(5)
	v_mfma_f32_32x32x16_bf16 v[32:47], v[208:211], v[220:223], v[32:47]
	ds_read_b128 v[244:247], v188 offset:41568
	s_waitcnt lgkmcnt(7)
	v_mfma_f32_32x32x16_bf16 v[16:31], v[212:215], v[216:219], v[16:31]
	s_waitcnt lgkmcnt(6)
	v_mfma_f32_32x32x16_bf16 v[0:15], v[212:215], v[220:223], v[0:15]
	s_waitcnt lgkmcnt(0)
	s_barrier
	s_waitcnt vmcnt(4)
	s_waitcnt lgkmcnt(1)
	v_mfma_f32_32x32x16_bf16 v[112:127], v[224:227], v[240:243], v[112:127]
	ds_write_b128 v189, v[160:163]
	ds_write_b128 v189, v[128:131] offset:4608
	s_waitcnt lgkmcnt(2)
	v_mfma_f32_32x32x16_bf16 v[96:111], v[224:227], v[244:247], v[96:111]
	ds_write_b128 v189, v[132:135] offset:9216
	global_load_dwordx4 v[160:163], v190, s[38:39]
	s_waitcnt lgkmcnt(4)
	v_mfma_f32_32x32x16_bf16 v[80:95], v[228:231], v[240:243], v[80:95]
	ds_write_b128 v189, v[136:139] offset:13824
	ds_write_b128 v189, v[140:143] offset:18432
	global_load_dwordx4 v[128:131], v191, s[38:39]
	s_waitcnt lgkmcnt(5)
	v_mfma_f32_32x32x16_bf16 v[64:79], v[228:231], v[244:247], v[64:79]
	ds_write_b128 v189, v[144:147] offset:23040
	global_load_dwordx4 v[132:135], v192, s[38:39]
	s_waitcnt lgkmcnt(7)
	v_mfma_f32_32x32x16_bf16 v[48:63], v[232:235], v[240:243], v[48:63]
	ds_write_b128 v189, v[148:151] offset:27648
	ds_write_b128 v189, v[156:159] offset:32256
	global_load_dwordx4 v[136:139], v193, s[38:39]
	s_waitcnt lgkmcnt(8)
	v_mfma_f32_32x32x16_bf16 v[32:47], v[232:235], v[244:247], v[32:47]
	s_waitcnt vmcnt(4)
	ds_write_b128 v189, v[152:155] offset:36864
	global_load_dwordx4 v[140:143], v194, s[38:39]
	s_waitcnt lgkmcnt(10)
	v_mfma_f32_32x32x16_bf16 v[16:31], v[236:239], v[240:243], v[16:31]
	ds_write_b128 v189, v[164:167] offset:41472
	ds_write_b128 v189, v[168:171] offset:46080
	global_load_dwordx4 v[144:147], v195, s[38:39]
	s_waitcnt lgkmcnt(11)
	v_mfma_f32_32x32x16_bf16 v[0:15], v[236:239], v[244:247], v[0:15]
	ds_write_b128 v189, v[172:175] offset:50688
	global_load_dwordx4 v[148:151], v196, s[38:39]
	global_load_dwordx4 v[156:159], v197, s[38:39]
	s_waitcnt lgkmcnt(0)
	s_barrier
	s_cmpk_lg_i32 s12, 0x780
	s_cbranch_scc1 .LBB0_1977
	ds_read_b128 v[216:219], v188 offset:36864
	ds_read_b128 v[200:203], v187
	ds_read_b128 v[220:223], v188 offset:41472
	ds_read_b128 v[204:207], v187 offset:4608
	ds_read_b128 v[208:211], v187 offset:9216
	ds_read_b128 v[212:215], v176
	s_waitcnt lgkmcnt(4)
	v_mfma_f32_32x32x16_bf16 v[112:127], v[200:203], v[216:219], v[112:127]
	ds_read_b128 v[240:243], v188 offset:36896
	s_waitcnt lgkmcnt(4)
	v_mfma_f32_32x32x16_bf16 v[96:111], v[200:203], v[220:223], v[96:111]
	ds_read_b128 v[224:227], v187 offset:32
	s_waitcnt lgkmcnt(4)
	v_mfma_f32_32x32x16_bf16 v[80:95], v[204:207], v[216:219], v[80:95]
	ds_read_b128 v[244:247], v188 offset:41504
	s_waitcnt lgkmcnt(5)
	v_mfma_f32_32x32x16_bf16 v[64:79], v[204:207], v[220:223], v[64:79]
	ds_read_b128 v[228:231], v187 offset:4640
	s_waitcnt lgkmcnt(5)
	v_mfma_f32_32x32x16_bf16 v[48:63], v[208:211], v[216:219], v[48:63]
	ds_read_b128 v[232:235], v187 offset:9248
	s_waitcnt lgkmcnt(6)
	v_mfma_f32_32x32x16_bf16 v[32:47], v[208:211], v[220:223], v[32:47]
	ds_read_b128 v[236:239], v176 offset:32
	s_waitcnt lgkmcnt(6)
	v_mfma_f32_32x32x16_bf16 v[16:31], v[212:215], v[216:219], v[16:31]
	s_waitcnt lgkmcnt(6)
	v_mfma_f32_32x32x16_bf16 v[0:15], v[212:215], v[220:223], v[0:15]
	s_waitcnt lgkmcnt(4)
	v_mfma_f32_32x32x16_bf16 v[112:127], v[224:227], v[240:243], v[112:127]
	ds_read_b128 v[200:203], v187 offset:64
	s_waitcnt lgkmcnt(4)
	v_mfma_f32_32x32x16_bf16 v[96:111], v[224:227], v[244:247], v[96:111]
	ds_read_b128 v[204:207], v187 offset:4672
	s_waitcnt lgkmcnt(4)
	v_mfma_f32_32x32x16_bf16 v[80:95], v[228:231], v[240:243], v[80:95]
	ds_read_b128 v[208:211], v187 offset:9280
	s_waitcnt lgkmcnt(5)
	v_mfma_f32_32x32x16_bf16 v[64:79], v[228:231], v[244:247], v[64:79]
	ds_read_b128 v[212:215], v176 offset:64
	s_waitcnt lgkmcnt(5)
	v_mfma_f32_32x32x16_bf16 v[48:63], v[232:235], v[240:243], v[48:63]
	ds_read_b128 v[216:219], v188 offset:36928
	s_waitcnt lgkmcnt(6)
	v_mfma_f32_32x32x16_bf16 v[32:47], v[232:235], v[244:247], v[32:47]
	ds_read_b128 v[220:223], v188 offset:41536
	s_waitcnt lgkmcnt(6)
	v_mfma_f32_32x32x16_bf16 v[16:31], v[236:239], v[240:243], v[16:31]
	s_waitcnt lgkmcnt(6)
	v_mfma_f32_32x32x16_bf16 v[0:15], v[236:239], v[244:247], v[0:15]
	s_waitcnt lgkmcnt(1)
	v_mfma_f32_32x32x16_bf16 v[112:127], v[200:203], v[216:219], v[112:127]
	ds_read_b128 v[224:227], v187 offset:96
	s_waitcnt lgkmcnt(1)
	v_mfma_f32_32x32x16_bf16 v[96:111], v[200:203], v[220:223], v[96:111]
	ds_read_b128 v[228:231], v187 offset:4704
	s_waitcnt lgkmcnt(3)
	v_mfma_f32_32x32x16_bf16 v[80:95], v[204:207], v[216:219], v[80:95]
	ds_read_b128 v[232:235], v187 offset:9312
	s_waitcnt lgkmcnt(3)
	v_mfma_f32_32x32x16_bf16 v[64:79], v[204:207], v[220:223], v[64:79]
	ds_read_b128 v[236:239], v176 offset:96
	s_waitcnt lgkmcnt(5)
	v_mfma_f32_32x32x16_bf16 v[48:63], v[208:211], v[216:219], v[48:63]
	ds_read_b128 v[240:243], v188 offset:36960
	s_waitcnt lgkmcnt(5)
	v_mfma_f32_32x32x16_bf16 v[32:47], v[208:211], v[220:223], v[32:47]
	ds_read_b128 v[244:247], v188 offset:41568
	s_waitcnt lgkmcnt(7)
	v_mfma_f32_32x32x16_bf16 v[16:31], v[212:215], v[216:219], v[16:31]
	s_waitcnt lgkmcnt(6)
	v_mfma_f32_32x32x16_bf16 v[0:15], v[212:215], v[220:223], v[0:15]
	s_waitcnt lgkmcnt(1)
	v_mfma_f32_32x32x16_bf16 v[112:127], v[224:227], v[240:243], v[112:127]
	s_waitcnt lgkmcnt(0)
	v_mfma_f32_32x32x16_bf16 v[96:111], v[224:227], v[244:247], v[96:111]
	s_waitcnt lgkmcnt(1)
	v_mfma_f32_32x32x16_bf16 v[80:95], v[228:231], v[240:243], v[80:95]
	s_waitcnt lgkmcnt(0)
	v_mfma_f32_32x32x16_bf16 v[64:79], v[228:231], v[244:247], v[64:79]
	s_waitcnt lgkmcnt(1)
	v_mfma_f32_32x32x16_bf16 v[48:63], v[232:235], v[240:243], v[48:63]
	s_waitcnt lgkmcnt(0)
	v_mfma_f32_32x32x16_bf16 v[32:47], v[232:235], v[244:247], v[32:47]
	s_waitcnt lgkmcnt(1)
	v_mfma_f32_32x32x16_bf16 v[16:31], v[236:239], v[240:243], v[16:31]
	s_waitcnt lgkmcnt(0)
	v_mfma_f32_32x32x16_bf16 v[0:15], v[236:239], v[244:247], v[0:15]
	s_waitcnt vmcnt(0)
	s_mul_i32 s42, s6, 0x2000
	s_add_u32 s44, s30, s42
	s_addc_u32 s45, s31, 0
	s_lshl_b32 s42, s58, 1
	s_add_u32 s44, s44, s42
	s_addc_u32 s45, s45, 0
	s_add_u32 s44, s44, 0x7157900
	s_addc_u32 s45, s45, 0
	s_mov_b32 s43, 1
	v_max_f32_e32 v112, 0, v112
	v_max_f32_e32 v113, 0, v113
	v_mul_f32_e32 v112, v112, v112
	v_mul_f32_e32 v113, v113, v113
	v_cvt_pk_bf16_f32 v190, v112, v113
	v_max_f32_e32 v114, 0, v114
	v_max_f32_e32 v115, 0, v115
	v_mul_f32_e32 v114, v114, v114
	v_mul_f32_e32 v115, v115, v115
	v_cvt_pk_bf16_f32 v191, v114, v115
	v_max_f32_e32 v116, 0, v116
	v_max_f32_e32 v117, 0, v117
	v_mul_f32_e32 v116, v116, v116
	v_mul_f32_e32 v117, v117, v117
	v_cvt_pk_bf16_f32 v192, v116, v117
	v_max_f32_e32 v118, 0, v118
	v_max_f32_e32 v119, 0, v119
	v_mul_f32_e32 v118, v118, v118
	v_mul_f32_e32 v119, v119, v119
	v_cvt_pk_bf16_f32 v193, v118, v119
	v_max_f32_e32 v120, 0, v120
	v_max_f32_e32 v121, 0, v121
	v_mul_f32_e32 v120, v120, v120
	v_mul_f32_e32 v121, v121, v121
	v_cvt_pk_bf16_f32 v194, v120, v121
	v_max_f32_e32 v122, 0, v122
	v_max_f32_e32 v123, 0, v123
	v_mul_f32_e32 v122, v122, v122
	v_mul_f32_e32 v123, v123, v123
	v_cvt_pk_bf16_f32 v195, v122, v123
	v_max_f32_e32 v124, 0, v124
	v_max_f32_e32 v125, 0, v125
	v_mul_f32_e32 v124, v124, v124
	v_mul_f32_e32 v125, v125, v125
	v_cvt_pk_bf16_f32 v196, v124, v125
	v_max_f32_e32 v126, 0, v126
	v_max_f32_e32 v127, 0, v127
	v_mul_f32_e32 v126, v126, v126
	v_mul_f32_e32 v127, v127, v127
	v_cvt_pk_bf16_f32 v197, v126, v127
	v_max_f32_e32 v96, 0, v96
	v_max_f32_e32 v97, 0, v97
	v_mul_f32_e32 v96, v96, v96
	v_mul_f32_e32 v97, v97, v97
	v_cvt_pk_bf16_f32 v198, v96, v97
	v_max_f32_e32 v98, 0, v98
	v_max_f32_e32 v99, 0, v99
	v_mul_f32_e32 v98, v98, v98
	v_mul_f32_e32 v99, v99, v99
	v_cvt_pk_bf16_f32 v199, v98, v99
	v_max_f32_e32 v100, 0, v100
	v_max_f32_e32 v101, 0, v101
	v_mul_f32_e32 v100, v100, v100
	v_mul_f32_e32 v101, v101, v101
	v_cvt_pk_bf16_f32 v200, v100, v101
	v_max_f32_e32 v102, 0, v102
	v_max_f32_e32 v103, 0, v103
	v_mul_f32_e32 v102, v102, v102
	v_mul_f32_e32 v103, v103, v103
	v_cvt_pk_bf16_f32 v201, v102, v103
	v_max_f32_e32 v104, 0, v104
	v_max_f32_e32 v105, 0, v105
	v_mul_f32_e32 v104, v104, v104
	v_mul_f32_e32 v105, v105, v105
	v_cvt_pk_bf16_f32 v202, v104, v105
	v_max_f32_e32 v106, 0, v106
	v_max_f32_e32 v107, 0, v107
	v_mul_f32_e32 v106, v106, v106
	v_mul_f32_e32 v107, v107, v107
	v_cvt_pk_bf16_f32 v203, v106, v107
	v_max_f32_e32 v108, 0, v108
	v_max_f32_e32 v109, 0, v109
	v_mul_f32_e32 v108, v108, v108
	v_mul_f32_e32 v109, v109, v109
	v_cvt_pk_bf16_f32 v204, v108, v109
	v_max_f32_e32 v110, 0, v110
	v_max_f32_e32 v111, 0, v111
	v_mul_f32_e32 v110, v110, v110
	v_mul_f32_e32 v111, v111, v111
	v_cvt_pk_bf16_f32 v205, v110, v111
	v_max_f32_e32 v80, 0, v80
	v_max_f32_e32 v81, 0, v81
	v_mul_f32_e32 v80, v80, v80
	v_mul_f32_e32 v81, v81, v81
	v_cvt_pk_bf16_f32 v206, v80, v81
	v_max_f32_e32 v82, 0, v82
	v_max_f32_e32 v83, 0, v83
	v_mul_f32_e32 v82, v82, v82
	v_mul_f32_e32 v83, v83, v83
	v_cvt_pk_bf16_f32 v207, v82, v83
	v_max_f32_e32 v84, 0, v84
	v_max_f32_e32 v85, 0, v85
	v_mul_f32_e32 v84, v84, v84
	v_mul_f32_e32 v85, v85, v85
	v_cvt_pk_bf16_f32 v208, v84, v85
	v_max_f32_e32 v86, 0, v86
	v_max_f32_e32 v87, 0, v87
	v_mul_f32_e32 v86, v86, v86
	v_mul_f32_e32 v87, v87, v87
	v_cvt_pk_bf16_f32 v209, v86, v87
	v_max_f32_e32 v88, 0, v88
	v_max_f32_e32 v89, 0, v89
	v_mul_f32_e32 v88, v88, v88
	v_mul_f32_e32 v89, v89, v89
	v_cvt_pk_bf16_f32 v210, v88, v89
	v_max_f32_e32 v90, 0, v90
	v_max_f32_e32 v91, 0, v91
	v_mul_f32_e32 v90, v90, v90
	v_mul_f32_e32 v91, v91, v91
	v_cvt_pk_bf16_f32 v211, v90, v91
	v_max_f32_e32 v92, 0, v92
	v_max_f32_e32 v93, 0, v93
	v_mul_f32_e32 v92, v92, v92
	v_mul_f32_e32 v93, v93, v93
	v_cvt_pk_bf16_f32 v212, v92, v93
	v_max_f32_e32 v94, 0, v94
	v_max_f32_e32 v95, 0, v95
	v_mul_f32_e32 v94, v94, v94
	v_mul_f32_e32 v95, v95, v95
	v_cvt_pk_bf16_f32 v213, v94, v95
	v_max_f32_e32 v64, 0, v64
	v_max_f32_e32 v65, 0, v65
	v_mul_f32_e32 v64, v64, v64
	v_mul_f32_e32 v65, v65, v65
	v_cvt_pk_bf16_f32 v214, v64, v65
	v_max_f32_e32 v66, 0, v66
	v_max_f32_e32 v67, 0, v67
	v_mul_f32_e32 v66, v66, v66
	v_mul_f32_e32 v67, v67, v67
	v_cvt_pk_bf16_f32 v215, v66, v67
	v_max_f32_e32 v68, 0, v68
	v_max_f32_e32 v69, 0, v69
	v_mul_f32_e32 v68, v68, v68
	v_mul_f32_e32 v69, v69, v69
	v_cvt_pk_bf16_f32 v216, v68, v69
	v_max_f32_e32 v70, 0, v70
	v_max_f32_e32 v71, 0, v71
	v_mul_f32_e32 v70, v70, v70
	v_mul_f32_e32 v71, v71, v71
	v_cvt_pk_bf16_f32 v217, v70, v71
	v_max_f32_e32 v72, 0, v72
	v_max_f32_e32 v73, 0, v73
	v_mul_f32_e32 v72, v72, v72
	v_mul_f32_e32 v73, v73, v73
	v_cvt_pk_bf16_f32 v218, v72, v73
	v_max_f32_e32 v74, 0, v74
	v_max_f32_e32 v75, 0, v75
	v_mul_f32_e32 v74, v74, v74
	v_mul_f32_e32 v75, v75, v75
	v_cvt_pk_bf16_f32 v219, v74, v75
	v_max_f32_e32 v76, 0, v76
	v_max_f32_e32 v77, 0, v77
	v_mul_f32_e32 v76, v76, v76
	v_mul_f32_e32 v77, v77, v77
	v_cvt_pk_bf16_f32 v220, v76, v77
	v_max_f32_e32 v78, 0, v78
	v_max_f32_e32 v79, 0, v79
	v_mul_f32_e32 v78, v78, v78
	v_mul_f32_e32 v79, v79, v79
	v_cvt_pk_bf16_f32 v221, v78, v79
	v_max_f32_e32 v48, 0, v48
	v_max_f32_e32 v49, 0, v49
	v_mul_f32_e32 v48, v48, v48
	v_mul_f32_e32 v49, v49, v49
	v_cvt_pk_bf16_f32 v222, v48, v49
	v_max_f32_e32 v50, 0, v50
	v_max_f32_e32 v51, 0, v51
	v_mul_f32_e32 v50, v50, v50
	v_mul_f32_e32 v51, v51, v51
	v_cvt_pk_bf16_f32 v223, v50, v51
	v_max_f32_e32 v52, 0, v52
	v_max_f32_e32 v53, 0, v53
	v_mul_f32_e32 v52, v52, v52
	v_mul_f32_e32 v53, v53, v53
	v_cvt_pk_bf16_f32 v224, v52, v53
	v_max_f32_e32 v54, 0, v54
	v_max_f32_e32 v55, 0, v55
	v_mul_f32_e32 v54, v54, v54
	v_mul_f32_e32 v55, v55, v55
	v_cvt_pk_bf16_f32 v225, v54, v55
	v_max_f32_e32 v56, 0, v56
	v_max_f32_e32 v57, 0, v57
	v_mul_f32_e32 v56, v56, v56
	v_mul_f32_e32 v57, v57, v57
	v_cvt_pk_bf16_f32 v226, v56, v57
	v_max_f32_e32 v58, 0, v58
	v_max_f32_e32 v59, 0, v59
	v_mul_f32_e32 v58, v58, v58
	v_mul_f32_e32 v59, v59, v59
	v_cvt_pk_bf16_f32 v227, v58, v59
	v_max_f32_e32 v60, 0, v60
	v_max_f32_e32 v61, 0, v61
	v_mul_f32_e32 v60, v60, v60
	v_mul_f32_e32 v61, v61, v61
	v_cvt_pk_bf16_f32 v228, v60, v61
	v_max_f32_e32 v62, 0, v62
	v_max_f32_e32 v63, 0, v63
	v_mul_f32_e32 v62, v62, v62
	v_mul_f32_e32 v63, v63, v63
	v_cvt_pk_bf16_f32 v229, v62, v63
	v_max_f32_e32 v32, 0, v32
	v_max_f32_e32 v33, 0, v33
	v_mul_f32_e32 v32, v32, v32
	v_mul_f32_e32 v33, v33, v33
	v_cvt_pk_bf16_f32 v230, v32, v33
	v_max_f32_e32 v34, 0, v34
	v_max_f32_e32 v35, 0, v35
	v_mul_f32_e32 v34, v34, v34
	v_mul_f32_e32 v35, v35, v35
	v_cvt_pk_bf16_f32 v231, v34, v35
	v_max_f32_e32 v36, 0, v36
	v_max_f32_e32 v37, 0, v37
	v_mul_f32_e32 v36, v36, v36
	v_mul_f32_e32 v37, v37, v37
	v_cvt_pk_bf16_f32 v232, v36, v37
	v_max_f32_e32 v38, 0, v38
	v_max_f32_e32 v39, 0, v39
	v_mul_f32_e32 v38, v38, v38
	v_mul_f32_e32 v39, v39, v39
	v_cvt_pk_bf16_f32 v233, v38, v39
	v_max_f32_e32 v40, 0, v40
	v_max_f32_e32 v41, 0, v41
	v_mul_f32_e32 v40, v40, v40
	v_mul_f32_e32 v41, v41, v41
	v_cvt_pk_bf16_f32 v234, v40, v41
	v_max_f32_e32 v42, 0, v42
	v_max_f32_e32 v43, 0, v43
	v_mul_f32_e32 v42, v42, v42
	v_mul_f32_e32 v43, v43, v43
	v_cvt_pk_bf16_f32 v235, v42, v43
	v_max_f32_e32 v44, 0, v44
	v_max_f32_e32 v45, 0, v45
	v_mul_f32_e32 v44, v44, v44
	v_mul_f32_e32 v45, v45, v45
	v_cvt_pk_bf16_f32 v236, v44, v45
	v_max_f32_e32 v46, 0, v46
	v_max_f32_e32 v47, 0, v47
	v_mul_f32_e32 v46, v46, v46
	v_mul_f32_e32 v47, v47, v47
	v_cvt_pk_bf16_f32 v237, v46, v47
	v_max_f32_e32 v16, 0, v16
	v_max_f32_e32 v17, 0, v17
	v_mul_f32_e32 v16, v16, v16
	v_mul_f32_e32 v17, v17, v17
	v_cvt_pk_bf16_f32 v238, v16, v17
	v_max_f32_e32 v18, 0, v18
	v_max_f32_e32 v19, 0, v19
	v_mul_f32_e32 v18, v18, v18
	v_mul_f32_e32 v19, v19, v19
	v_cvt_pk_bf16_f32 v239, v18, v19
	v_max_f32_e32 v20, 0, v20
	v_max_f32_e32 v21, 0, v21
	v_mul_f32_e32 v20, v20, v20
	v_mul_f32_e32 v21, v21, v21
	v_cvt_pk_bf16_f32 v240, v20, v21
	v_max_f32_e32 v22, 0, v22
	v_max_f32_e32 v23, 0, v23
	v_mul_f32_e32 v22, v22, v22
	v_mul_f32_e32 v23, v23, v23
	v_cvt_pk_bf16_f32 v241, v22, v23
	v_max_f32_e32 v24, 0, v24
	v_max_f32_e32 v25, 0, v25
	v_mul_f32_e32 v24, v24, v24
	v_mul_f32_e32 v25, v25, v25
	v_cvt_pk_bf16_f32 v242, v24, v25
	v_max_f32_e32 v26, 0, v26
	v_max_f32_e32 v27, 0, v27
	v_mul_f32_e32 v26, v26, v26
	v_mul_f32_e32 v27, v27, v27
	v_cvt_pk_bf16_f32 v243, v26, v27
	v_max_f32_e32 v28, 0, v28
	v_max_f32_e32 v29, 0, v29
	v_mul_f32_e32 v28, v28, v28
	v_mul_f32_e32 v29, v29, v29
	v_cvt_pk_bf16_f32 v244, v28, v29
	v_max_f32_e32 v30, 0, v30
	v_max_f32_e32 v31, 0, v31
	v_mul_f32_e32 v30, v30, v30
	v_mul_f32_e32 v31, v31, v31
	v_cvt_pk_bf16_f32 v245, v30, v31
	v_max_f32_e32 v0, 0, v0
	v_max_f32_e32 v1, 0, v1
	v_mul_f32_e32 v0, v0, v0
	v_mul_f32_e32 v1, v1, v1
	v_cvt_pk_bf16_f32 v246, v0, v1
	v_max_f32_e32 v2, 0, v2
	v_max_f32_e32 v3, 0, v3
	v_mul_f32_e32 v2, v2, v2
	v_mul_f32_e32 v3, v3, v3
	v_cvt_pk_bf16_f32 v247, v2, v3
	v_max_f32_e32 v4, 0, v4
	v_max_f32_e32 v5, 0, v5
	v_mul_f32_e32 v4, v4, v4
	v_mul_f32_e32 v5, v5, v5
	v_cvt_pk_bf16_f32 v248, v4, v5
	v_max_f32_e32 v6, 0, v6
	v_max_f32_e32 v7, 0, v7
	v_mul_f32_e32 v6, v6, v6
	v_mul_f32_e32 v7, v7, v7
	v_cvt_pk_bf16_f32 v249, v6, v7
	v_max_f32_e32 v8, 0, v8
	v_max_f32_e32 v9, 0, v9
	v_mul_f32_e32 v8, v8, v8
	v_mul_f32_e32 v9, v9, v9
	v_cvt_pk_bf16_f32 v250, v8, v9
	v_max_f32_e32 v10, 0, v10
	v_max_f32_e32 v11, 0, v11
	v_mul_f32_e32 v10, v10, v10
	v_mul_f32_e32 v11, v11, v11
	v_cvt_pk_bf16_f32 v251, v10, v11
	v_max_f32_e32 v12, 0, v12
	v_max_f32_e32 v13, 0, v13
	v_mul_f32_e32 v12, v12, v12
	v_mul_f32_e32 v13, v13, v13
	v_cvt_pk_bf16_f32 v252, v12, v13
	v_max_f32_e32 v14, 0, v14
	v_max_f32_e32 v15, 0, v15
	v_mul_f32_e32 v14, v14, v14
	v_mul_f32_e32 v15, v15, v15
	v_cvt_pk_bf16_f32 v253, v14, v15
	s_add_i32 s57, s57, s21
	s_add_i32 s56, s56, s21
	s_cmpk_lt_u32 s57, 0x200
	s_cbranch_scc1 .LBB0_1976
	v_and_b32_e32 v3, 15, v182
	v_lshrrev_b32_e32 v4, 4, v182
	v_mul_u32_u24_e32 v2, 0x2000, v4
	v_lshl_add_u32 v2, v3, 4, v2
	v_mul_u32_u24_e32 v1, 0x110, v4
	v_lshl_add_u32 v1, v3, 4, v1
	v_lshrrev_b32_e32 v3, 7, v182
	v_bfe_u32 v4, v182, 5, 1
	v_lshlrev_b32_e32 v3, 6, v3
	v_lshl_or_b32 v3, v4, 2, v3
	v_mul_u32_u24_e32 v3, 136, v3
	v_and_b32_e32 v4, 0x5f, v182
	v_add_lshl_u32 v0, v3, v4, 1
	s_barrier
	ds_write_b16 v0, v190
	ds_write_b16_d16_hi v0, v190 offset:272
	ds_write_b16 v0, v191 offset:544
	ds_write_b16_d16_hi v0, v191 offset:816
	ds_write_b16 v0, v192 offset:2176
	ds_write_b16_d16_hi v0, v192 offset:2448
	ds_write_b16 v0, v193 offset:2720
	ds_write_b16_d16_hi v0, v193 offset:2992
	ds_write_b16 v0, v194 offset:4352
	ds_write_b16_d16_hi v0, v194 offset:4624
	ds_write_b16 v0, v195 offset:4896
	ds_write_b16_d16_hi v0, v195 offset:5168
	ds_write_b16 v0, v196 offset:6528
	ds_write_b16_d16_hi v0, v196 offset:6800
	ds_write_b16 v0, v197 offset:7072
	ds_write_b16_d16_hi v0, v197 offset:7344
	ds_write_b16 v0, v198 offset:64
	ds_write_b16_d16_hi v0, v198 offset:336
	ds_write_b16 v0, v199 offset:608
	ds_write_b16_d16_hi v0, v199 offset:880
	ds_write_b16 v0, v200 offset:2240
	ds_write_b16_d16_hi v0, v200 offset:2512
	ds_write_b16 v0, v201 offset:2784
	ds_write_b16_d16_hi v0, v201 offset:3056
	ds_write_b16 v0, v202 offset:4416
	ds_write_b16_d16_hi v0, v202 offset:4688
	ds_write_b16 v0, v203 offset:4960
	ds_write_b16_d16_hi v0, v203 offset:5232
	ds_write_b16 v0, v204 offset:6592
	ds_write_b16_d16_hi v0, v204 offset:6864
	ds_write_b16 v0, v205 offset:7136
	ds_write_b16_d16_hi v0, v205 offset:7408
	ds_write_b16 v0, v206 offset:8704
	ds_write_b16_d16_hi v0, v206 offset:8976
	ds_write_b16 v0, v207 offset:9248
	ds_write_b16_d16_hi v0, v207 offset:9520
	ds_write_b16 v0, v208 offset:10880
	ds_write_b16_d16_hi v0, v208 offset:11152
	ds_write_b16 v0, v209 offset:11424
	ds_write_b16_d16_hi v0, v209 offset:11696
	ds_write_b16 v0, v210 offset:13056
	ds_write_b16_d16_hi v0, v210 offset:13328
	ds_write_b16 v0, v211 offset:13600
	ds_write_b16_d16_hi v0, v211 offset:13872
	ds_write_b16 v0, v212 offset:15232
	ds_write_b16_d16_hi v0, v212 offset:15504
	ds_write_b16 v0, v213 offset:15776
	ds_write_b16_d16_hi v0, v213 offset:16048
	ds_write_b16 v0, v214 offset:8768
	ds_write_b16_d16_hi v0, v214 offset:9040
	ds_write_b16 v0, v215 offset:9312
	ds_write_b16_d16_hi v0, v215 offset:9584
	ds_write_b16 v0, v216 offset:10944
	ds_write_b16_d16_hi v0, v216 offset:11216
	ds_write_b16 v0, v217 offset:11488
	ds_write_b16_d16_hi v0, v217 offset:11760
	ds_write_b16 v0, v218 offset:13120
	ds_write_b16_d16_hi v0, v218 offset:13392
	ds_write_b16 v0, v219 offset:13664
	ds_write_b16_d16_hi v0, v219 offset:13936
	ds_write_b16 v0, v220 offset:15296
	ds_write_b16_d16_hi v0, v220 offset:15568
	ds_write_b16 v0, v221 offset:15840
	ds_write_b16_d16_hi v0, v221 offset:16112
	s_waitcnt lgkmcnt(0)
	s_barrier
	ds_read_b128 v[8:11], v1
	ds_read_b128 v[12:15], v1 offset:4352
	ds_read_b128 v[16:19], v1 offset:8704
	ds_read_b128 v[20:23], v1 offset:13056
	ds_read_b128 v[24:27], v1 offset:17408
	ds_read_b128 v[28:31], v1 offset:21760
	ds_read_b128 v[32:35], v1 offset:26112
	ds_read_b128 v[36:39], v1 offset:30464
	s_add_u32 s38, s44, 0x0
	s_addc_u32 s39, s45, 0
	s_waitcnt lgkmcnt(7)
	global_store_dwordx4 v2, v[8:11], s[38:39]
	s_add_u32 s38, s44, 0x20000
	s_addc_u32 s39, s45, 0
	s_waitcnt lgkmcnt(6)
	global_store_dwordx4 v2, v[12:15], s[38:39]
	s_add_u32 s38, s44, 0x40000
	s_addc_u32 s39, s45, 0
	s_waitcnt lgkmcnt(5)
	global_store_dwordx4 v2, v[16:19], s[38:39]
	s_add_u32 s38, s44, 0x60000
	s_addc_u32 s39, s45, 0
	s_waitcnt lgkmcnt(4)
	global_store_dwordx4 v2, v[20:23], s[38:39]
	s_add_u32 s38, s44, 0x100000
	s_addc_u32 s39, s45, 0
	s_waitcnt lgkmcnt(3)
	global_store_dwordx4 v2, v[24:27], s[38:39]
	s_add_u32 s38, s44, 0x120000
	s_addc_u32 s39, s45, 0
	s_waitcnt lgkmcnt(2)
	global_store_dwordx4 v2, v[28:31], s[38:39]
	s_add_u32 s38, s44, 0x140000
	s_addc_u32 s39, s45, 0
	s_waitcnt lgkmcnt(1)
	global_store_dwordx4 v2, v[32:35], s[38:39]
	s_add_u32 s38, s44, 0x160000
	s_addc_u32 s39, s45, 0
	s_waitcnt lgkmcnt(0)
	global_store_dwordx4 v2, v[36:39], s[38:39]
	s_barrier
	ds_write_b16 v0, v222
	ds_write_b16_d16_hi v0, v222 offset:272
	ds_write_b16 v0, v223 offset:544
	ds_write_b16_d16_hi v0, v223 offset:816
	ds_write_b16 v0, v224 offset:2176
	ds_write_b16_d16_hi v0, v224 offset:2448
	ds_write_b16 v0, v225 offset:2720
	ds_write_b16_d16_hi v0, v225 offset:2992
	ds_write_b16 v0, v226 offset:4352
	ds_write_b16_d16_hi v0, v226 offset:4624
	ds_write_b16 v0, v227 offset:4896
	ds_write_b16_d16_hi v0, v227 offset:5168
	ds_write_b16 v0, v228 offset:6528
	ds_write_b16_d16_hi v0, v228 offset:6800
	ds_write_b16 v0, v229 offset:7072
	ds_write_b16_d16_hi v0, v229 offset:7344
	ds_write_b16 v0, v230 offset:64
	ds_write_b16_d16_hi v0, v230 offset:336
	ds_write_b16 v0, v231 offset:608
	ds_write_b16_d16_hi v0, v231 offset:880
	ds_write_b16 v0, v232 offset:2240
	ds_write_b16_d16_hi v0, v232 offset:2512
	ds_write_b16 v0, v233 offset:2784
	ds_write_b16_d16_hi v0, v233 offset:3056
	ds_write_b16 v0, v234 offset:4416
	ds_write_b16_d16_hi v0, v234 offset:4688
	ds_write_b16 v0, v235 offset:4960
	ds_write_b16_d16_hi v0, v235 offset:5232
	ds_write_b16 v0, v236 offset:6592
	ds_write_b16_d16_hi v0, v236 offset:6864
	ds_write_b16 v0, v237 offset:7136
	ds_write_b16_d16_hi v0, v237 offset:7408
	ds_write_b16 v0, v238 offset:8704
	ds_write_b16_d16_hi v0, v238 offset:8976
	ds_write_b16 v0, v239 offset:9248
	ds_write_b16_d16_hi v0, v239 offset:9520
	ds_write_b16 v0, v240 offset:10880
	ds_write_b16_d16_hi v0, v240 offset:11152
	ds_write_b16 v0, v241 offset:11424
	ds_write_b16_d16_hi v0, v241 offset:11696
	ds_write_b16 v0, v242 offset:13056
	ds_write_b16_d16_hi v0, v242 offset:13328
	ds_write_b16 v0, v243 offset:13600
	ds_write_b16_d16_hi v0, v243 offset:13872
	ds_write_b16 v0, v244 offset:15232
	ds_write_b16_d16_hi v0, v244 offset:15504
	ds_write_b16 v0, v245 offset:15776
	ds_write_b16_d16_hi v0, v245 offset:16048
	ds_write_b16 v0, v246 offset:8768
	ds_write_b16_d16_hi v0, v246 offset:9040
	ds_write_b16 v0, v247 offset:9312
	ds_write_b16_d16_hi v0, v247 offset:9584
	ds_write_b16 v0, v248 offset:10944
	ds_write_b16_d16_hi v0, v248 offset:11216
	ds_write_b16 v0, v249 offset:11488
	ds_write_b16_d16_hi v0, v249 offset:11760
	ds_write_b16 v0, v250 offset:13120
	ds_write_b16_d16_hi v0, v250 offset:13392
	ds_write_b16 v0, v251 offset:13664
	ds_write_b16_d16_hi v0, v251 offset:13936
	ds_write_b16 v0, v252 offset:15296
	ds_write_b16_d16_hi v0, v252 offset:15568
	ds_write_b16 v0, v253 offset:15840
	ds_write_b16_d16_hi v0, v253 offset:16112
	s_waitcnt lgkmcnt(0)
	s_barrier
	ds_read_b128 v[8:11], v1
	ds_read_b128 v[12:15], v1 offset:4352
	ds_read_b128 v[16:19], v1 offset:8704
	ds_read_b128 v[20:23], v1 offset:13056
	ds_read_b128 v[24:27], v1 offset:17408
	ds_read_b128 v[28:31], v1 offset:21760
	ds_read_b128 v[32:35], v1 offset:26112
	ds_read_b128 v[36:39], v1 offset:30464
	s_add_u32 s38, s44, 0x80000
	s_addc_u32 s39, s45, 0
	s_waitcnt lgkmcnt(7)
	global_store_dwordx4 v2, v[8:11], s[38:39]
	s_add_u32 s38, s44, 0xa0000
	s_addc_u32 s39, s45, 0
	s_waitcnt lgkmcnt(6)
	global_store_dwordx4 v2, v[12:15], s[38:39]
	s_add_u32 s38, s44, 0xc0000
	s_addc_u32 s39, s45, 0
	s_waitcnt lgkmcnt(5)
	global_store_dwordx4 v2, v[16:19], s[38:39]
	s_add_u32 s38, s44, 0xe0000
	s_addc_u32 s39, s45, 0
	s_waitcnt lgkmcnt(4)
	global_store_dwordx4 v2, v[20:23], s[38:39]
	s_add_u32 s38, s44, 0x180000
	s_addc_u32 s39, s45, 0
	s_waitcnt lgkmcnt(3)
	global_store_dwordx4 v2, v[24:27], s[38:39]
	s_add_u32 s38, s44, 0x1a0000
	s_addc_u32 s39, s45, 0
	s_waitcnt lgkmcnt(2)
	global_store_dwordx4 v2, v[28:31], s[38:39]
	s_add_u32 s38, s44, 0x1c0000
	s_addc_u32 s39, s45, 0
	s_waitcnt lgkmcnt(1)
	global_store_dwordx4 v2, v[32:35], s[38:39]
	s_add_u32 s38, s44, 0x1e0000
	s_addc_u32 s39, s45, 0
	s_waitcnt lgkmcnt(0)
	global_store_dwordx4 v2, v[36:39], s[38:39]
	s_mov_b32 s43, 0
	s_branch .LBB0_1969
